# glr_pre GLA items: the 32 per-token loads issued in two groups with cloned address arithmetic (was about 10 serialized round trips per item)
# speedup vs baseline: 1.0021x; 1.0007x over previous
.LBB0_436:
	s_mul_hi_i32 s12, s91, 0x2aaaaaab
	s_lshr_b32 s13, s12, 31
	s_ashr_i32 s12, s12, 2
	s_add_i32 s82, s12, s13
	s_mul_i32 s12, s82, 0xffffffe8
	s_add_i32 s76, s91, s12
	s_mov_b64 s[12:13], -1
	s_cmp_gt_i32 s76, 15
	v_lshl_add_u32 v103, s82, 5, v67
	s_cbranch_scc0 .LBB0_510
	v_mov_b32_e32 v155, v97
	s_add_i32 s12, s76, -16
	s_lshr_b32 s38, s12, 1
	s_and_b32 s28, s94, 2
	v_or_b32_e32 v146, s28, v63
	s_movk_i32 s26, 0x810
	v_cmp_gt_i32_e64 s[14:15], s26, v103
	s_mul_i32 s33, s38, 0x810
	s_nop 1
	v_cndmask_b32_e64 v140, 0, v103, s[14:15]
	v_add_u32_e32 v142, s33, v140
	v_mov_b64_e32 v[140:141], s[54:55]
	v_mad_i64_i32 v[144:145], s[16:17], v142, s44, v[140:141]
	v_lshlrev_b32_e32 v142, 1, v62
	v_lshl_or_b32 v142, v146, 7, v142
	v_or_b32_e32 v154, 0x2200, v142
	v_lshl_add_u64 v[146:147], v[144:145], 0, v[154:155]
	v_mov_b32_e32 v143, v155
	s_mov_b64 s[86:87], 0x2a00
	global_load_ushort v139, v[146:147], off
	v_lshl_add_u64 v[146:147], v[144:145], 0, v[142:143]
	v_lshl_add_u64 v[152:153], v[144:145], 0, s[86:87]
	v_add_co_u32_e32 v144, vcc, s74, v144
	s_nop 1
	v_addc_co_u32_e32 v145, vcc, 0, v145, vcc
	global_load_dwordx4 v[160:163], v[144:145], off offset:2560
	global_load_dwordx4 v[164:167], v[152:153], off offset:16
	v_or_b32_e32 v156, 2, v103
	v_cmp_gt_i32_e64 s[12:13], s26, v156
	v_or_b32_e32 v150, 3, v103
	v_or_b32_e32 v144, 1, v103
	v_cmp_gt_i32_e64 s[18:19], s26, v144
	v_cmp_gt_i32_e64 s[16:17], s26, v150
	s_nop 1
	v_cndmask_b32_e64 v144, 0, v144, s[18:19]
	v_add_u32_e32 v157, s33, v144
	v_mad_i64_i32 v[148:149], s[20:21], v157, s44, v[140:141]
	v_lshl_add_u64 v[144:145], v[148:149], 0, v[154:155]
	global_load_ushort v159, v[144:145], off
	v_lshl_add_u64 v[144:145], v[148:149], 0, v[142:143]
	v_lshl_add_u64 v[152:153], v[148:149], 0, s[86:87]
	v_add_co_u32_e32 v148, vcc, s74, v148
	s_nop 1
	v_addc_co_u32_e32 v149, vcc, 0, v149, vcc
	global_load_dwordx4 v[168:171], v[148:149], off offset:2560
	global_load_dwordx4 v[172:175], v[152:153], off offset:16
	v_cndmask_b32_e64 v148, 0, v156, s[12:13]
	v_add_u32_e32 v148, s33, v148
	v_mad_i64_i32 v[148:149], s[20:21], v148, s44, v[140:141]
	v_add_co_u32_e32 v146, vcc, s74, v146
	v_lshl_add_u64 v[152:153], v[148:149], 0, v[154:155]
	s_nop 1
	v_addc_co_u32_e32 v147, vcc, 0, v147, vcc
	global_load_ushort v176, v[152:153], off
	global_load_ushort v177, v[146:147], off offset:1024
	v_lshl_add_u64 v[152:153], v[148:149], 0, v[142:143]
	v_add_co_u32_e32 v146, vcc, s74, v152
	s_nop 1
	v_addc_co_u32_e32 v147, vcc, 0, v153, vcc
	global_load_ushort v178, v[146:147], off offset:1024
	v_lshl_add_u64 v[146:147], v[148:149], 0, s[86:87]
	v_add_co_u32_e32 v148, vcc, s74, v148
	s_nop 1
	v_addc_co_u32_e32 v149, vcc, 0, v149, vcc
	global_load_dwordx4 v[180:183], v[148:149], off offset:2560
	global_load_dwordx4 v[184:187], v[146:147], off offset:16
	v_cndmask_b32_e64 v146, 0, v150, s[16:17]
	v_add_u32_e32 v158, s33, v146
	v_mad_i64_i32 v[146:147], s[20:21], v158, s44, v[140:141]
	v_lshl_add_u64 v[150:151], v[146:147], 0, v[154:155]
	global_load_ushort v179, v[150:151], off
	v_lshl_add_u64 v[150:151], v[146:147], 0, v[142:143]
	v_add_co_u32_e32 v150, vcc, s74, v150
	s_nop 1
	v_addc_co_u32_e32 v151, vcc, 0, v151, vcc
	v_add_co_u32_e32 v144, vcc, s74, v144
	global_load_ushort v188, v[150:151], off offset:1024
	s_nop 1
	v_addc_co_u32_e32 v145, vcc, 0, v145, vcc
	global_load_ushort v189, v[144:145], off offset:1024
	v_lshl_add_u64 v[150:151], v[146:147], 0, s[86:87]
	v_add_co_u32_e32 v144, vcc, s74, v146
	s_nop 1
	v_addc_co_u32_e32 v145, vcc, 0, v147, vcc
	global_load_dwordx4 v[190:193], v[144:145], off offset:2560
	global_load_dwordx4 v[194:197], v[150:151], off offset:16
	s_add_i32 s12, s76, -16
	s_lshr_b32 s38, s12, 1
	s_and_b32 s28, s94, 2
	s_lshl_b32 s60, s38, 2
	v_or_b32_e32 v6, s28, v63
	s_add_i32 s60, s60, 32
	s_ashr_i32 s83, s82, 31
	v_or_b32_e32 v2, s60, v6
	v_mov_b64_e32 v[0:1], s[82:83]
	v_mad_u64_u32 v[0:1], s[12:13], v2, s79, v[0:1]
	v_mov_b64_e32 v[2:3], s[56:57]
	v_mad_u64_u32 v[38:39], s[12:13], v0, s44, v[2:3]
	v_lshlrev_b32_e32 v96, 8, v6
	v_mad_i32_i24 v39, v1, s44, v39
	v_lshl_add_u64 v[0:1], v[10:11], 0, v[96:97]
	global_load_dword v107, v[0:1], off
	v_lshl_add_u64 v[0:1], v[12:13], 0, v[96:97]
	s_movk_i32 s12, 0x1000
	v_add_co_u32_e32 v2, vcc, s12, v0
	global_load_dword v44, v[0:1], off
	global_load_dword v46, v[0:1], off offset:1024
	global_load_dword v42, v[0:1], off offset:2048
	global_load_dword v40, v[0:1], off offset:3072
	v_addc_co_u32_e32 v3, vcc, 0, v1, vcc
	v_add_co_u32_e32 v4, vcc, s74, v0
	s_movk_i32 s26, 0x810
	s_nop 0
	v_addc_co_u32_e32 v5, vcc, 0, v1, vcc
	v_add_co_u32_e32 v0, vcc, s44, v0
	v_cmp_gt_i32_e64 s[14:15], s26, v103
	s_nop 0
	v_addc_co_u32_e32 v1, vcc, 0, v1, vcc
	global_load_dword v54, v[4:5], off offset:-4096
	global_load_dword v52, v[2:3], off offset:1024
	global_load_dword v50, v[2:3], off offset:2048
	global_load_dword v48, v[2:3], off offset:3072
	global_load_dword v45, v[4:5], off
	global_load_dword v47, v[4:5], off offset:1024
	global_load_dword v43, v[4:5], off offset:2048
	global_load_dword v41, v[4:5], off offset:3072
	global_load_dword v55, v[0:1], off
	global_load_dword v53, v[0:1], off offset:1024
	global_load_dword v51, v[0:1], off offset:2048
	global_load_dword v49, v[0:1], off offset:3072
	s_mul_i32 s33, s38, 0x810
	v_cndmask_b32_e64 v0, 0, v103, s[14:15]
	v_add_u32_e32 v2, s33, v0
	v_mov_b64_e32 v[0:1], s[54:55]
	v_mad_i64_i32 v[4:5], s[16:17], v2, s44, v[0:1]
	v_lshlrev_b32_e32 v2, 1, v62
	v_lshl_or_b32 v2, v6, 7, v2
	v_or_b32_e32 v96, 0x2200, v2
	v_lshl_add_u64 v[6:7], v[4:5], 0, v[96:97]
	v_mov_b32_e32 v3, v97
	s_mov_b64 s[86:87], 0x2a00
	s_waitcnt vmcnt(0)
	v_mov_b32_e32 v106, v139
	v_lshl_add_u64 v[6:7], v[4:5], 0, v[2:3]
	v_lshl_add_u64 v[60:61], v[4:5], 0, s[86:87]
	v_add_co_u32_e32 v4, vcc, s74, v4
	s_mov_b32 s29, 0xbfb8aa3b
	s_nop 0
	v_addc_co_u32_e32 v5, vcc, 0, v5, vcc
	v_mov_b64_e32 v[56:57], v[160:161]
	v_mov_b64_e32 v[58:59], v[162:163]
	v_mov_b64_e32 v[108:109], v[164:165]
	v_mov_b64_e32 v[110:111], v[166:167]
	s_mov_b32 s49, 0x3f317217
	s_mov_b32 s61, 0x7f800000
	v_mov_b32_e32 v136, 0x41b17218
	v_or_b32_e32 v104, 2, v103
	v_cmp_gt_i32_e64 s[12:13], s26, v104
	s_waitcnt vmcnt(0)
	v_and_b32_e32 v60, 0xffff0000, v56
	v_and_b32_e32 v61, 0xffff0000, v108
	v_lshlrev_b32_e32 v4, 16, v56
	v_lshlrev_b32_e32 v5, 16, v108
	v_pk_mul_f32 v[60:61], v[46:47], v[60:61]
	v_lshlrev_b32_e32 v56, 16, v58
	v_pk_fma_f32 v[4:5], v[44:45], v[4:5], v[60:61]
	v_lshlrev_b32_e32 v60, 16, v57
	v_lshlrev_b32_e32 v61, 16, v109
	v_pk_fma_f32 v[4:5], v[42:43], v[60:61], v[4:5]
	v_and_b32_e32 v61, 0xffff0000, v109
	v_and_b32_e32 v60, 0xffff0000, v57
	v_pk_fma_f32 v[4:5], v[40:41], v[60:61], v[4:5]
	v_lshlrev_b32_e32 v57, 16, v110
	v_pk_fma_f32 v[4:5], v[54:55], v[56:57], v[4:5]
	v_and_b32_e32 v57, 0xffff0000, v110
	v_and_b32_e32 v56, 0xffff0000, v58
	v_pk_fma_f32 v[4:5], v[52:53], v[56:57], v[4:5]
	v_lshlrev_b32_e32 v56, 16, v59
	v_lshlrev_b32_e32 v57, 16, v111
	v_pk_fma_f32 v[4:5], v[50:51], v[56:57], v[4:5]
	v_and_b32_e32 v57, 0xffff0000, v111
	v_and_b32_e32 v56, 0xffff0000, v59
	v_pk_fma_f32 v[4:5], v[48:49], v[56:57], v[4:5]
	v_or_b32_e32 v58, 3, v103
	v_add_f32_e32 v4, v107, v4
	v_add_f32_e32 v4, v4, v5
	v_min_f32_e32 v5, 0, v4
	v_mul_f32_e64 v4, |v4|, s29
	v_exp_f32_e32 v4, v4
	s_nop 0
	v_add_f32_e32 v4, 1.0, v4
	v_cmp_gt_f32_e32 vcc, s45, v4
	s_nop 1
	v_cndmask_b32_e64 v56, 0, 32, vcc
	v_ldexp_f32 v4, v4, v56
	v_log_f32_e32 v4, v4
	s_nop 0
	v_mul_f32_e32 v56, 0x3f317217, v4
	v_fma_f32 v56, v4, s49, -v56
	v_fmac_f32_e32 v56, 0x3377d1cf, v4
	v_fmac_f32_e32 v56, 0x3f317217, v4
	v_cmp_lt_f32_e64 s[16:17], |v4|, s61
	s_nop 1
	v_cndmask_b32_e64 v4, v4, v56, s[16:17]
	v_cndmask_b32_e32 v56, 0, v136, vcc
	v_sub_f32_e32 v4, v4, v56
	v_sub_f32_e32 v4, v5, v4
	s_mov_b32 s16, 0x3d800000
	v_fma_f32 v4, v4, s16, 0
	v_cndmask_b32_e64 v108, 0, v4, s[14:15]
	v_or_b32_e32 v4, 1, v103
	v_cmp_gt_i32_e64 s[18:19], s26, v4
	v_cmp_gt_i32_e64 s[16:17], s26, v58
	s_nop 0
	v_cndmask_b32_e64 v4, 0, v4, s[18:19]
	v_add_u32_e32 v105, s33, v4
	v_mad_i64_i32 v[56:57], s[20:21], v105, s44, v[0:1]
	v_lshl_add_u64 v[4:5], v[56:57], 0, v[96:97]
	v_mov_b32_e32 v109, v159
	v_lshl_add_u64 v[4:5], v[56:57], 0, v[2:3]
	v_lshl_add_u64 v[60:61], v[56:57], 0, s[86:87]
	v_add_co_u32_e32 v56, vcc, s74, v56
	s_nop 1
	v_addc_co_u32_e32 v57, vcc, 0, v57, vcc
	v_mov_b64_e32 v[110:111], v[168:169]
	v_mov_b64_e32 v[112:113], v[170:171]
	v_mov_b64_e32 v[114:115], v[172:173]
	v_mov_b64_e32 v[116:117], v[174:175]
	s_waitcnt vmcnt(0)
	v_and_b32_e32 v60, 0xffff0000, v110
	s_waitcnt vmcnt(0)
	v_and_b32_e32 v61, 0xffff0000, v114
	v_lshlrev_b32_e32 v56, 16, v110
	v_lshlrev_b32_e32 v57, 16, v114
	v_pk_mul_f32 v[60:61], v[46:47], v[60:61]
	s_nop 0
	v_pk_fma_f32 v[56:57], v[44:45], v[56:57], v[60:61]
	v_lshlrev_b32_e32 v60, 16, v111
	v_lshlrev_b32_e32 v61, 16, v115
	v_pk_fma_f32 v[56:57], v[42:43], v[60:61], v[56:57]
	v_and_b32_e32 v61, 0xffff0000, v115
	v_and_b32_e32 v60, 0xffff0000, v111
	v_pk_fma_f32 v[56:57], v[40:41], v[60:61], v[56:57]
	v_lshlrev_b32_e32 v60, 16, v112
	v_lshlrev_b32_e32 v61, 16, v116
	v_pk_fma_f32 v[56:57], v[54:55], v[60:61], v[56:57]
	v_and_b32_e32 v61, 0xffff0000, v116
	v_and_b32_e32 v60, 0xffff0000, v112
	v_pk_fma_f32 v[56:57], v[52:53], v[60:61], v[56:57]
	v_lshlrev_b32_e32 v60, 16, v113
	v_lshlrev_b32_e32 v61, 16, v117
	v_pk_fma_f32 v[56:57], v[50:51], v[60:61], v[56:57]
	v_and_b32_e32 v61, 0xffff0000, v117
	v_and_b32_e32 v60, 0xffff0000, v113
	v_pk_fma_f32 v[56:57], v[48:49], v[60:61], v[56:57]
	s_nop 0
	v_add_f32_e32 v56, v107, v56
	v_add_f32_e32 v56, v56, v57
	v_min_f32_e32 v57, 0, v56
	v_mul_f32_e64 v56, |v56|, s29
	v_exp_f32_e32 v56, v56
	s_nop 0
	v_add_f32_e32 v56, 1.0, v56
	v_cmp_gt_f32_e32 vcc, s45, v56
	s_nop 1
	v_cndmask_b32_e64 v59, 0, 32, vcc
	v_ldexp_f32 v56, v56, v59
	v_log_f32_e32 v56, v56
	s_nop 0
	v_mul_f32_e32 v59, 0x3f317217, v56
	v_fma_f32 v59, v56, s49, -v59
	v_fmac_f32_e32 v59, 0x3377d1cf, v56
	v_fmac_f32_e32 v59, 0x3f317217, v56
	v_cmp_lt_f32_e64 s[20:21], |v56|, s61
	s_nop 1
	v_cndmask_b32_e64 v56, v56, v59, s[20:21]
	v_cndmask_b32_e32 v59, 0, v136, vcc
	v_sub_f32_e32 v56, v56, v59
	v_sub_f32_e32 v56, v57, v56
	v_mul_f32_e32 v56, 0x3d800000, v56
	v_cndmask_b32_e64 v56, 0, v56, s[18:19]
	v_add_f32_e32 v112, v108, v56
	v_cndmask_b32_e64 v56, 0, v104, s[12:13]
	v_add_u32_e32 v56, s33, v56
	v_mad_i64_i32 v[56:57], s[20:21], v56, s44, v[0:1]
	v_add_co_u32_e32 v6, vcc, s74, v6
	v_lshl_add_u64 v[60:61], v[56:57], 0, v[96:97]
	s_nop 0
	v_addc_co_u32_e32 v7, vcc, 0, v7, vcc
	v_mov_b32_e32 v113, v176
	v_mov_b32_e32 v59, v177
	v_lshl_add_u64 v[60:61], v[56:57], 0, v[2:3]
	v_add_co_u32_e32 v6, vcc, s74, v60
	s_waitcnt vmcnt(0)
	v_lshlrev_b32_e32 v59, 16, v59
	v_addc_co_u32_e32 v7, vcc, 0, v61, vcc
	v_mov_b32_e32 v6, v178
	s_waitcnt vmcnt(0)
	v_lshlrev_b32_e32 v60, 16, v6
	v_lshl_add_u64 v[6:7], v[56:57], 0, s[86:87]
	v_add_co_u32_e32 v56, vcc, s74, v56
	s_nop 1
	v_addc_co_u32_e32 v57, vcc, 0, v57, vcc
	v_mov_b64_e32 v[114:115], v[180:181]
	v_mov_b64_e32 v[116:117], v[182:183]
	v_mov_b64_e32 v[118:119], v[184:185]
	v_mov_b64_e32 v[120:121], v[186:187]
	s_waitcnt vmcnt(0)
	v_and_b32_e32 v56, 0xffff0000, v114
	s_waitcnt vmcnt(0)
	v_and_b32_e32 v57, 0xffff0000, v118
	v_lshlrev_b32_e32 v6, 16, v114
	v_lshlrev_b32_e32 v7, 16, v118
	v_pk_mul_f32 v[56:57], v[46:47], v[56:57]
	s_nop 0
	v_pk_fma_f32 v[6:7], v[44:45], v[6:7], v[56:57]
	v_lshlrev_b32_e32 v56, 16, v115
	v_lshlrev_b32_e32 v57, 16, v119
	v_pk_fma_f32 v[6:7], v[42:43], v[56:57], v[6:7]
	v_and_b32_e32 v57, 0xffff0000, v119
	v_and_b32_e32 v56, 0xffff0000, v115
	v_pk_fma_f32 v[6:7], v[40:41], v[56:57], v[6:7]
	v_lshlrev_b32_e32 v56, 16, v116
	v_lshlrev_b32_e32 v57, 16, v120
	v_pk_fma_f32 v[6:7], v[54:55], v[56:57], v[6:7]
	v_and_b32_e32 v57, 0xffff0000, v120
	v_and_b32_e32 v56, 0xffff0000, v116
	v_pk_fma_f32 v[6:7], v[52:53], v[56:57], v[6:7]
	v_lshlrev_b32_e32 v56, 16, v117
	v_lshlrev_b32_e32 v57, 16, v121
	v_pk_fma_f32 v[6:7], v[50:51], v[56:57], v[6:7]
	v_and_b32_e32 v57, 0xffff0000, v121
	v_and_b32_e32 v56, 0xffff0000, v117
	v_pk_fma_f32 v[6:7], v[48:49], v[56:57], v[6:7]
	v_cndmask_b32_e64 v57, 0, v60, s[12:13]
	v_add_f32_e32 v6, v107, v6
	v_add_f32_e32 v6, v6, v7
	v_min_f32_e32 v7, 0, v6
	v_mul_f32_e64 v6, |v6|, s29
	v_exp_f32_e32 v6, v6
	s_nop 0
	v_add_f32_e32 v6, 1.0, v6
	v_cmp_gt_f32_e32 vcc, s45, v6
	s_nop 1
	v_cndmask_b32_e64 v56, 0, 32, vcc
	v_ldexp_f32 v6, v6, v56
	v_log_f32_e32 v6, v6
	s_nop 0
	v_mul_f32_e32 v56, 0x3f317217, v6
	v_fma_f32 v56, v6, s49, -v56
	v_fmac_f32_e32 v56, 0x3377d1cf, v6
	v_fmac_f32_e32 v56, 0x3f317217, v6
	v_cmp_lt_f32_e64 s[20:21], |v6|, s61
	s_nop 1
	v_cndmask_b32_e64 v6, v6, v56, s[20:21]
	v_cndmask_b32_e32 v56, 0, v136, vcc
	v_sub_f32_e32 v6, v6, v56
	v_sub_f32_e32 v6, v7, v6
	v_mul_f32_e32 v6, 0x3d800000, v6
	v_cndmask_b32_e64 v6, 0, v6, s[12:13]
	v_add_f32_e32 v116, v112, v6
	v_cndmask_b32_e64 v6, 0, v58, s[16:17]
	v_add_u32_e32 v110, s33, v6
	v_mad_i64_i32 v[6:7], s[20:21], v110, s44, v[0:1]
	v_cndmask_b32_e64 v56, 0, v59, s[14:15]
	v_lshl_add_u64 v[58:59], v[6:7], 0, v[96:97]
	v_mov_b32_e32 v115, v179
	v_lshl_add_u64 v[58:59], v[6:7], 0, v[2:3]
	v_add_co_u32_e32 v58, vcc, s74, v58
	s_nop 1
	v_addc_co_u32_e32 v59, vcc, 0, v59, vcc
	v_add_co_u32_e32 v4, vcc, s74, v4
	v_mov_b32_e32 v58, v188
	s_nop 0
	v_addc_co_u32_e32 v5, vcc, 0, v5, vcc
	v_mov_b32_e32 v4, v189
	s_waitcnt vmcnt(0)
	v_lshlrev_b32_e32 v114, 16, v58
	v_lshl_add_u64 v[58:59], v[6:7], 0, s[86:87]
	s_waitcnt vmcnt(0)
	v_lshlrev_b32_e32 v111, 16, v4
	v_add_co_u32_e32 v4, vcc, s74, v6
	s_nop 1
	v_addc_co_u32_e32 v5, vcc, 0, v7, vcc
	v_mov_b64_e32 v[4:5], v[190:191]
	v_mov_b64_e32 v[6:7], v[192:193]
	s_nop 0
	v_mov_b64_e32 v[58:59], v[194:195]
	v_mov_b64_e32 v[60:61], v[196:197]
	v_mov_b32_e32 v140, v0
	v_mov_b32_e32 v141, v1
	v_mov_b32_e32 v142, v2
	v_mov_b32_e32 v143, v3
	v_or_b32_e32 v150, 4, v103
	v_cmp_gt_i32_e64 s[22:23], s26, v150
	v_or_b32_e32 v139, 6, v103
	s_nop 1
	v_cndmask_b32_e64 v144, 0, v150, s[22:23]
	v_add_u32_e32 v144, s33, v144
	v_mad_i64_i32 v[146:147], s[24:25], v144, s44, v[140:141]
	v_lshl_add_u64 v[144:145], v[146:147], 0, v[96:97]
	global_load_ushort v152, v[144:145], off
	v_lshl_add_u64 v[144:145], v[146:147], 0, v[142:143]
	v_lshl_add_u64 v[148:149], v[146:147], 0, s[86:87]
	v_add_co_u32_e32 v146, vcc, s74, v146
	v_cmp_gt_i32_e64 s[20:21], s26, v139
	s_nop 1
	v_addc_co_u32_e32 v147, vcc, 0, v147, vcc
	global_load_dwordx4 v[158:161], v[146:147], off offset:2560
	global_load_dwordx4 v[162:165], v[148:149], off offset:16
	v_or_b32_e32 v153, 7, v103
	v_or_b32_e32 v146, 5, v103
	v_cmp_gt_i32_e64 s[24:25], s26, v153
	v_cmp_gt_i32_e64 s[98:99], s26, v146
	s_nop 1
	v_cndmask_b32_e64 v146, 0, v146, s[98:99]
	v_add_u32_e32 v151, s33, v146
	v_mad_i64_i32 v[148:149], s[30:31], v151, s44, v[140:141]
	v_lshl_add_u64 v[146:147], v[148:149], 0, v[96:97]
	global_load_ushort v166, v[146:147], off
	v_lshl_add_u64 v[146:147], v[148:149], 0, v[142:143]
	v_lshl_add_u64 v[156:157], v[148:149], 0, s[86:87]
	v_add_co_u32_e32 v148, vcc, s74, v148
	s_nop 1
	v_addc_co_u32_e32 v149, vcc, 0, v149, vcc
	global_load_dwordx4 v[168:171], v[148:149], off offset:2560
	global_load_dwordx4 v[172:175], v[156:157], off offset:16
	v_cndmask_b32_e64 v148, 0, v139, s[20:21]
	v_add_u32_e32 v148, s33, v148
	v_mad_i64_i32 v[148:149], s[30:31], v148, s44, v[140:141]
	v_lshl_add_u64 v[154:155], v[148:149], 0, v[96:97]
	global_load_ushort v167, v[154:155], off
	v_lshl_add_u64 v[154:155], v[148:149], 0, v[142:143]
	v_add_co_u32_e32 v154, vcc, s74, v154
	s_nop 1
	v_addc_co_u32_e32 v155, vcc, 0, v155, vcc
	v_add_co_u32_e32 v144, vcc, s74, v144
	global_load_ushort v176, v[154:155], off offset:1024
	s_nop 1
	v_addc_co_u32_e32 v145, vcc, 0, v145, vcc
	global_load_ushort v177, v[144:145], off offset:1024
	v_lshl_add_u64 v[144:145], v[148:149], 0, s[86:87]
	v_add_co_u32_e32 v148, vcc, s74, v148
	s_nop 1
	v_addc_co_u32_e32 v149, vcc, 0, v149, vcc
	global_load_dwordx4 v[178:181], v[148:149], off offset:2560
	global_load_dwordx4 v[182:185], v[144:145], off offset:16
	v_cndmask_b32_e64 v144, 0, v153, s[24:25]
	v_add_u32_e32 v153, s33, v144
	v_mad_i64_i32 v[140:141], s[30:31], v153, s44, v[140:141]
	v_lshl_add_u64 v[142:143], v[140:141], 0, v[142:143]
	v_add_co_u32_e32 v142, vcc, s74, v142
	v_lshl_add_u64 v[144:145], v[140:141], 0, v[96:97]
	s_nop 1
	v_addc_co_u32_e32 v143, vcc, 0, v143, vcc
	global_load_ushort v186, v[144:145], off
	global_load_ushort v187, v[142:143], off offset:1024
	v_add_co_u32_e32 v142, vcc, s74, v146
	s_nop 1
	v_addc_co_u32_e32 v143, vcc, 0, v147, vcc
	global_load_ushort v188, v[142:143], off offset:1024
	v_lshl_add_u64 v[144:145], v[140:141], 0, s[86:87]
	v_add_co_u32_e32 v140, vcc, s74, v140
	s_nop 1
	v_addc_co_u32_e32 v141, vcc, 0, v141, vcc
	global_load_dwordx4 v[190:193], v[140:141], off offset:2560
	global_load_dwordx4 v[194:197], v[144:145], off offset:16
	s_waitcnt vmcnt(0)
	v_and_b32_e32 v120, 0xffff0000, v4
	s_waitcnt vmcnt(0)
	v_and_b32_e32 v121, 0xffff0000, v58
	v_lshlrev_b32_e32 v118, 16, v4
	v_lshlrev_b32_e32 v119, 16, v58
	v_pk_mul_f32 v[120:121], v[46:47], v[120:121]
	v_and_b32_e32 v58, 0xffff0000, v5
	v_pk_fma_f32 v[118:119], v[44:45], v[118:119], v[120:121]
	v_lshlrev_b32_e32 v120, 16, v5
	v_lshlrev_b32_e32 v121, 16, v59
	v_pk_fma_f32 v[118:119], v[42:43], v[120:121], v[118:119]
	v_and_b32_e32 v59, 0xffff0000, v59
	v_pk_fma_f32 v[4:5], v[40:41], v[58:59], v[118:119]
	v_lshlrev_b32_e32 v58, 16, v6
	v_lshlrev_b32_e32 v59, 16, v60
	v_pk_fma_f32 v[4:5], v[54:55], v[58:59], v[4:5]
	v_and_b32_e32 v59, 0xffff0000, v60
	v_and_b32_e32 v58, 0xffff0000, v6
	v_pk_fma_f32 v[4:5], v[52:53], v[58:59], v[4:5]
	v_lshlrev_b32_e32 v58, 16, v7
	v_lshlrev_b32_e32 v59, 16, v61
	v_pk_fma_f32 v[4:5], v[50:51], v[58:59], v[4:5]
	v_and_b32_e32 v59, 0xffff0000, v61
	v_and_b32_e32 v58, 0xffff0000, v7
	v_pk_fma_f32 v[4:5], v[48:49], v[58:59], v[4:5]
	v_cndmask_b32_e64 v59, 0, v114, s[16:17]
	v_add_f32_e32 v4, v107, v4
	v_add_f32_e32 v4, v4, v5
	v_min_f32_e32 v5, 0, v4
	v_mul_f32_e64 v4, |v4|, s29
	v_exp_f32_e32 v4, v4
	v_or_b32_e32 v114, 4, v103
	v_cmp_gt_i32_e64 s[22:23], s26, v114
	v_cndmask_b32_e64 v58, 0, v111, s[18:19]
	v_add_f32_e32 v4, 1.0, v4
	v_cmp_gt_f32_e32 vcc, s45, v4
	v_or_b32_e32 v111, 6, v103
	s_nop 0
	v_cndmask_b32_e64 v6, 0, 32, vcc
	v_ldexp_f32 v4, v4, v6
	v_log_f32_e32 v4, v4
	s_nop 0
	v_mul_f32_e32 v6, 0x3f317217, v4
	v_fma_f32 v6, v4, s49, -v6
	v_fmac_f32_e32 v6, 0x3377d1cf, v4
	v_fmac_f32_e32 v6, 0x3f317217, v4
	v_cmp_lt_f32_e64 s[20:21], |v4|, s61
	s_nop 1
	v_cndmask_b32_e64 v4, v4, v6, s[20:21]
	v_cndmask_b32_e32 v6, 0, v136, vcc
	v_sub_f32_e32 v4, v4, v6
	v_sub_f32_e32 v4, v5, v4
	v_mul_f32_e32 v4, 0x3d800000, v4
	v_cndmask_b32_e64 v4, 0, v4, s[16:17]
	v_add_f32_e32 v119, v116, v4
	v_cndmask_b32_e64 v4, 0, v114, s[22:23]
	v_add_u32_e32 v4, s33, v4
	v_mad_i64_i32 v[6:7], s[24:25], v4, s44, v[0:1]
	v_lshl_add_u64 v[4:5], v[6:7], 0, v[96:97]
	s_waitcnt vmcnt(0)
	v_mov_b32_e32 v118, v152
	v_lshl_add_u64 v[4:5], v[6:7], 0, v[2:3]
	v_lshl_add_u64 v[60:61], v[6:7], 0, s[86:87]
	v_add_co_u32_e32 v6, vcc, s74, v6
	v_cmp_gt_i32_e64 s[20:21], s26, v111
	s_nop 0
	v_addc_co_u32_e32 v7, vcc, 0, v7, vcc
	v_mov_b64_e32 v[120:121], v[158:159]
	v_mov_b64_e32 v[122:123], v[160:161]
	v_mov_b64_e32 v[124:125], v[162:163]
	v_mov_b64_e32 v[126:127], v[164:165]
	s_waitcnt vmcnt(0)
	v_and_b32_e32 v60, 0xffff0000, v120
	s_waitcnt vmcnt(0)
	v_and_b32_e32 v61, 0xffff0000, v124
	v_lshlrev_b32_e32 v6, 16, v120
	v_lshlrev_b32_e32 v7, 16, v124
	v_pk_mul_f32 v[60:61], v[46:47], v[60:61]
	s_nop 0
	v_pk_fma_f32 v[6:7], v[44:45], v[6:7], v[60:61]
	v_lshlrev_b32_e32 v60, 16, v121
	v_lshlrev_b32_e32 v61, 16, v125
	v_pk_fma_f32 v[6:7], v[42:43], v[60:61], v[6:7]
	v_and_b32_e32 v61, 0xffff0000, v125
	v_and_b32_e32 v60, 0xffff0000, v121
	v_pk_fma_f32 v[6:7], v[40:41], v[60:61], v[6:7]
	v_lshlrev_b32_e32 v60, 16, v122
	v_lshlrev_b32_e32 v61, 16, v126
	v_pk_fma_f32 v[6:7], v[54:55], v[60:61], v[6:7]
	v_and_b32_e32 v61, 0xffff0000, v126
	v_and_b32_e32 v60, 0xffff0000, v122
	v_pk_fma_f32 v[6:7], v[52:53], v[60:61], v[6:7]
	v_lshlrev_b32_e32 v60, 16, v123
	v_lshlrev_b32_e32 v61, 16, v127
	v_pk_fma_f32 v[6:7], v[50:51], v[60:61], v[6:7]
	v_and_b32_e32 v61, 0xffff0000, v127
	v_and_b32_e32 v60, 0xffff0000, v123
	v_pk_fma_f32 v[6:7], v[48:49], v[60:61], v[6:7]
	v_or_b32_e32 v123, 7, v103
	v_add_f32_e32 v6, v107, v6
	v_add_f32_e32 v6, v6, v7
	v_min_f32_e32 v7, 0, v6
	v_mul_f32_e64 v6, |v6|, s29
	v_exp_f32_e32 v6, v6
	s_nop 0
	v_add_f32_e32 v6, 1.0, v6
	v_cmp_gt_f32_e32 vcc, s45, v6
	s_nop 1
	v_cndmask_b32_e64 v60, 0, 32, vcc
	v_ldexp_f32 v6, v6, v60
	v_log_f32_e32 v6, v6
	s_nop 0
	v_mul_f32_e32 v60, 0x3f317217, v6
	v_fma_f32 v60, v6, s49, -v60
	v_fmac_f32_e32 v60, 0x3377d1cf, v6
	v_fmac_f32_e32 v60, 0x3f317217, v6
	v_cmp_lt_f32_e64 s[24:25], |v6|, s61
	s_nop 1
	v_cndmask_b32_e64 v6, v6, v60, s[24:25]
	v_cndmask_b32_e32 v60, 0, v136, vcc
	v_sub_f32_e32 v6, v6, v60
	v_sub_f32_e32 v6, v7, v6
	v_mul_f32_e32 v6, 0x3d800000, v6
	v_cndmask_b32_e64 v122, 0, v6, s[22:23]
	v_or_b32_e32 v6, 5, v103
	v_cmp_gt_i32_e64 s[24:25], s26, v123
	v_cmp_gt_i32_e64 s[26:27], s26, v6
	s_nop 1
	v_cndmask_b32_e64 v6, 0, v6, s[26:27]
	v_add_u32_e32 v117, s33, v6
	v_mad_i64_i32 v[60:61], s[30:31], v117, s44, v[0:1]
	v_lshl_add_u64 v[6:7], v[60:61], 0, v[96:97]
	v_mov_b32_e32 v120, v166
	v_lshl_add_u64 v[6:7], v[60:61], 0, v[2:3]
	v_lshl_add_u64 v[128:129], v[60:61], 0, s[86:87]
	v_add_co_u32_e32 v60, vcc, s74, v60
	s_nop 1
	v_addc_co_u32_e32 v61, vcc, 0, v61, vcc
	v_mov_b64_e32 v[124:125], v[168:169]
	v_mov_b64_e32 v[126:127], v[170:171]
	s_nop 0
	v_mov_b64_e32 v[128:129], v[172:173]
	v_mov_b64_e32 v[130:131], v[174:175]
	s_waitcnt vmcnt(0)
	v_and_b32_e32 v132, 0xffff0000, v124
	s_waitcnt vmcnt(0)
	v_and_b32_e32 v133, 0xffff0000, v128
	v_lshlrev_b32_e32 v60, 16, v124
	v_lshlrev_b32_e32 v61, 16, v128
	v_pk_mul_f32 v[132:133], v[46:47], v[132:133]
	v_and_b32_e32 v128, 0xffff0000, v125
	v_pk_fma_f32 v[60:61], v[44:45], v[60:61], v[132:133]
	v_lshlrev_b32_e32 v132, 16, v125
	v_lshlrev_b32_e32 v133, 16, v129
	v_pk_fma_f32 v[60:61], v[42:43], v[132:133], v[60:61]
	v_and_b32_e32 v129, 0xffff0000, v129
	v_pk_fma_f32 v[60:61], v[40:41], v[128:129], v[60:61]
	v_lshlrev_b32_e32 v124, 16, v126
	v_lshlrev_b32_e32 v125, 16, v130
	v_pk_fma_f32 v[60:61], v[54:55], v[124:125], v[60:61]
	v_and_b32_e32 v125, 0xffff0000, v130
	v_and_b32_e32 v124, 0xffff0000, v126
	v_pk_fma_f32 v[60:61], v[52:53], v[124:125], v[60:61]
	v_lshlrev_b32_e32 v124, 16, v127
	v_lshlrev_b32_e32 v125, 16, v131
	v_pk_fma_f32 v[60:61], v[50:51], v[124:125], v[60:61]
	v_and_b32_e32 v125, 0xffff0000, v131
	v_and_b32_e32 v124, 0xffff0000, v127
	v_pk_fma_f32 v[60:61], v[48:49], v[124:125], v[60:61]
	s_nop 0
	v_add_f32_e32 v60, v107, v60
	v_add_f32_e32 v60, v60, v61
	v_min_f32_e32 v61, 0, v60
	v_mul_f32_e64 v60, |v60|, s29
	v_exp_f32_e32 v60, v60
	s_nop 0
	v_add_f32_e32 v60, 1.0, v60
	v_cmp_gt_f32_e32 vcc, s45, v60
	s_nop 1
	v_cndmask_b32_e64 v121, 0, 32, vcc
	v_ldexp_f32 v60, v60, v121
	v_log_f32_e32 v60, v60
	s_nop 0
	v_mul_f32_e32 v121, 0x3f317217, v60
	v_fma_f32 v121, v60, s49, -v121
	v_fmac_f32_e32 v121, 0x3377d1cf, v60
	v_fmac_f32_e32 v121, 0x3f317217, v60
	v_cmp_lt_f32_e64 s[30:31], |v60|, s61
	s_nop 1
	v_cndmask_b32_e64 v60, v60, v121, s[30:31]
	v_cndmask_b32_e32 v121, 0, v136, vcc
	v_sub_f32_e32 v60, v60, v121
	v_sub_f32_e32 v60, v61, v60
	v_mul_f32_e32 v60, 0x3d800000, v60
	v_cndmask_b32_e64 v124, 0, v60, s[26:27]
	v_cndmask_b32_e64 v60, 0, v111, s[20:21]
	v_add_u32_e32 v60, s33, v60
	v_mad_i64_i32 v[60:61], s[30:31], v60, s44, v[0:1]
	v_lshl_add_u64 v[126:127], v[60:61], 0, v[96:97]
	v_mov_b32_e32 v121, v167
	v_lshl_add_u64 v[126:127], v[60:61], 0, v[2:3]
	v_add_co_u32_e32 v126, vcc, s74, v126
	s_nop 1
	v_addc_co_u32_e32 v127, vcc, 0, v127, vcc
	v_add_co_u32_e32 v4, vcc, s74, v4
	v_mov_b32_e32 v125, v176
	s_nop 0
	v_addc_co_u32_e32 v5, vcc, 0, v5, vcc
	v_mov_b32_e32 v4, v177
	s_waitcnt vmcnt(0)
	v_lshlrev_b32_e32 v135, 16, v125
	s_waitcnt vmcnt(0)
	v_lshlrev_b32_e32 v134, 16, v4
	v_lshl_add_u64 v[4:5], v[60:61], 0, s[86:87]
	v_add_co_u32_e32 v60, vcc, s74, v60
	s_nop 1
	v_addc_co_u32_e32 v61, vcc, 0, v61, vcc
	v_mov_b64_e32 v[126:127], v[178:179]
	v_mov_b64_e32 v[128:129], v[180:181]
	v_mov_b64_e32 v[130:131], v[182:183]
	v_mov_b64_e32 v[132:133], v[184:185]
	s_waitcnt vmcnt(0)
	v_and_b32_e32 v60, 0xffff0000, v126
	s_waitcnt vmcnt(0)
	v_and_b32_e32 v61, 0xffff0000, v130
	v_lshlrev_b32_e32 v4, 16, v126
	v_lshlrev_b32_e32 v5, 16, v130
	v_pk_mul_f32 v[60:61], v[46:47], v[60:61]
	s_nop 0
	v_pk_fma_f32 v[4:5], v[44:45], v[4:5], v[60:61]
	v_lshlrev_b32_e32 v60, 16, v127
	v_lshlrev_b32_e32 v61, 16, v131
	v_pk_fma_f32 v[4:5], v[42:43], v[60:61], v[4:5]
	v_and_b32_e32 v61, 0xffff0000, v131
	v_and_b32_e32 v60, 0xffff0000, v127
	v_pk_fma_f32 v[4:5], v[40:41], v[60:61], v[4:5]
	v_lshlrev_b32_e32 v60, 16, v128
	v_lshlrev_b32_e32 v61, 16, v132
	v_pk_fma_f32 v[4:5], v[54:55], v[60:61], v[4:5]
	v_and_b32_e32 v61, 0xffff0000, v132
	v_and_b32_e32 v60, 0xffff0000, v128
	v_pk_fma_f32 v[4:5], v[52:53], v[60:61], v[4:5]
	v_lshlrev_b32_e32 v60, 16, v129
	v_lshlrev_b32_e32 v61, 16, v133
	v_pk_fma_f32 v[4:5], v[50:51], v[60:61], v[4:5]
	v_and_b32_e32 v61, 0xffff0000, v133
	v_and_b32_e32 v60, 0xffff0000, v129
	v_pk_fma_f32 v[4:5], v[48:49], v[60:61], v[4:5]
	v_cndmask_b32_e64 v61, 0, v135, s[20:21]
	v_add_f32_e32 v4, v107, v4
	v_add_f32_e32 v4, v4, v5
	v_min_f32_e32 v5, 0, v4
	v_mul_f32_e64 v4, |v4|, s29
	v_exp_f32_e32 v4, v4
	s_nop 0
	v_add_f32_e32 v4, 1.0, v4
	v_cmp_gt_f32_e32 vcc, s45, v4
	s_nop 1
	v_cndmask_b32_e64 v60, 0, 32, vcc
	v_ldexp_f32 v4, v4, v60
	v_log_f32_e32 v4, v4
	s_nop 0
	v_mul_f32_e32 v60, 0x3f317217, v4
	v_fma_f32 v60, v4, s49, -v60
	v_fmac_f32_e32 v60, 0x3377d1cf, v4
	v_fmac_f32_e32 v60, 0x3f317217, v4
	v_cmp_lt_f32_e64 s[30:31], |v4|, s61
	s_nop 1
	v_cndmask_b32_e64 v4, v4, v60, s[30:31]
	v_cndmask_b32_e32 v60, 0, v136, vcc
	v_sub_f32_e32 v4, v4, v60
	v_sub_f32_e32 v4, v5, v4
	v_mul_f32_e32 v4, 0x3d800000, v4
	v_cndmask_b32_e64 v125, 0, v4, s[20:21]
	v_cndmask_b32_e64 v4, 0, v123, s[24:25]
	v_add_u32_e32 v123, s33, v4
	v_mad_i64_i32 v[0:1], s[30:31], v123, s44, v[0:1]
	v_lshl_add_u64 v[2:3], v[0:1], 0, v[2:3]
	v_add_co_u32_e32 v2, vcc, s74, v2
	v_lshl_add_u64 v[4:5], v[0:1], 0, v[96:97]
	s_nop 0
	v_addc_co_u32_e32 v3, vcc, 0, v3, vcc
	v_mov_b32_e32 v96, v186
	v_cndmask_b32_e64 v60, 0, v134, s[22:23]
	v_mov_b32_e32 v4, v187
	v_add_co_u32_e32 v2, vcc, s74, v6
	s_waitcnt vmcnt(0)
	v_lshlrev_b32_e32 v131, 16, v4
	v_addc_co_u32_e32 v3, vcc, 0, v7, vcc
	v_mov_b32_e32 v2, v188
	v_lshl_add_u64 v[4:5], v[0:1], 0, s[86:87]
	v_add_co_u32_e32 v0, vcc, s74, v0
	s_waitcnt vmcnt(0)
	v_lshlrev_b32_e32 v130, 16, v2
	v_addc_co_u32_e32 v1, vcc, 0, v1, vcc
	v_mov_b64_e32 v[0:1], v[190:191]
	v_mov_b64_e32 v[2:3], v[192:193]
	s_nop 0
	v_mov_b64_e32 v[4:5], v[194:195]
	v_mov_b64_e32 v[6:7], v[196:197]
	s_barrier
	s_waitcnt vmcnt(1)
	v_and_b32_e32 v128, 0xffff0000, v0
	s_waitcnt vmcnt(0)
	v_and_b32_e32 v129, 0xffff0000, v4
	v_lshlrev_b32_e32 v126, 16, v0
	v_lshlrev_b32_e32 v127, 16, v4
	v_pk_mul_f32 v[46:47], v[46:47], v[128:129]
	v_and_b32_e32 v4, 0xffff0000, v1
	v_pk_fma_f32 v[44:45], v[44:45], v[126:127], v[46:47]
	v_lshlrev_b32_e32 v46, 16, v1
	v_lshlrev_b32_e32 v47, 16, v5
	v_pk_fma_f32 v[42:43], v[42:43], v[46:47], v[44:45]
	v_and_b32_e32 v5, 0xffff0000, v5
	v_pk_fma_f32 v[0:1], v[40:41], v[4:5], v[42:43]
	v_lshlrev_b32_e32 v4, 16, v2
	v_lshlrev_b32_e32 v5, 16, v6
	v_pk_fma_f32 v[0:1], v[54:55], v[4:5], v[0:1]
	v_and_b32_e32 v5, 0xffff0000, v6
	v_and_b32_e32 v4, 0xffff0000, v2
	v_pk_fma_f32 v[0:1], v[52:53], v[4:5], v[0:1]
	v_lshlrev_b32_e32 v4, 16, v3
	v_lshlrev_b32_e32 v5, 16, v7
	v_pk_fma_f32 v[0:1], v[50:51], v[4:5], v[0:1]
	v_and_b32_e32 v5, 0xffff0000, v7
	v_and_b32_e32 v4, 0xffff0000, v3
	v_pk_fma_f32 v[0:1], v[48:49], v[4:5], v[0:1]
	v_add_f32_e32 v52, v119, v122
	v_add_f32_e32 v0, v107, v0
	v_add_f32_e32 v0, v0, v1
	v_min_f32_e32 v1, 0, v0
	v_mul_f32_e64 v0, |v0|, s29
	v_exp_f32_e32 v0, v0
	v_add_f32_e32 v53, v52, v124
	v_add_f32_e32 v54, v53, v125
	v_add_f32_e32 v0, 1.0, v0
	v_cmp_gt_f32_e32 vcc, s45, v0
	s_nop 1
	v_cndmask_b32_e64 v2, 0, 32, vcc
	v_ldexp_f32 v0, v0, v2
	v_log_f32_e32 v0, v0
	s_nop 0
	v_mul_f32_e32 v2, 0x3f317217, v0
	v_fma_f32 v2, v0, s49, -v2
	v_fmac_f32_e32 v2, 0x3377d1cf, v0
	v_fmac_f32_e32 v2, 0x3f317217, v0
	v_cmp_lt_f32_e64 s[30:31], |v0|, s61
	s_nop 1
	v_cndmask_b32_e64 v0, v0, v2, s[30:31]
	v_cndmask_b32_e32 v2, 0, v136, vcc
	v_sub_f32_e32 v0, v0, v2
	v_sub_f32_e32 v0, v1, v0
	v_mul_f32_e32 v0, 0x3d800000, v0
	v_cndmask_b32_e64 v2, 0, v0, s[24:25]
	v_add_f32_e32 v5, v54, v2
	ds_write_b32 v68, v5
	s_waitcnt lgkmcnt(0)
	s_barrier
	ds_read2st64_b32 v[6:7], v69 offset1:2
	ds_read2st64_b32 v[2:3], v69 offset0:4 offset1:6
	v_cndmask_b32_e64 v1, 0, v131, s[24:25]
	v_cndmask_b32_e64 v0, 0, v130, s[26:27]
	s_waitcnt lgkmcnt(1)
	v_add_f32_e32 v7, v6, v7
	s_waitcnt lgkmcnt(0)
	v_add_f32_e32 v4, v7, v2
	v_cndmask_b32_e64 v2, v4, v7, s[4:5]
	v_cndmask_b32_e64 v2, v2, v6, s[2:3]
	v_cndmask_b32_e64 v47, v2, 0, s[0:1]
	v_mov_b32_e32 v46, v3
	v_add_f32_e32 v45, v108, v47
	v_pk_add_f32 v[2:3], v[4:5], v[46:47]
	v_add_f32_e32 v44, v112, v47
	v_sub_f32_e32 v5, v2, v45
	v_mul_f32_e32 v5, 0x3fb8aa3b, v5
	v_exp_f32_e32 v40, v5
	v_sub_f32_e32 v5, v2, v44
	v_mul_f32_e32 v5, 0x3fb8aa3b, v5
	v_add_f32_e32 v43, v116, v47
	v_exp_f32_e32 v48, v5
	v_sub_f32_e32 v5, v2, v43
	v_mul_f32_e32 v5, 0x3fb8aa3b, v5
	v_exp_f32_e32 v41, v5
	v_add_f32_e32 v42, v119, v47
	v_sub_f32_e32 v5, v2, v42
	v_mul_f32_e32 v5, 0x3fb8aa3b, v5
	v_pk_mul_f32 v[50:51], v[56:57], v[40:41]
	v_add_f32_e32 v41, v52, v47
	v_exp_f32_e32 v49, v5
	v_sub_f32_e32 v5, v2, v41
	v_add_f32_e32 v40, v53, v47
	v_mul_f32_e32 v5, 0x3fb8aa3b, v5
	v_exp_f32_e32 v46, v5
	v_sub_f32_e32 v5, v2, v40
	v_mul_f32_e32 v5, 0x3fb8aa3b, v5
	v_exp_f32_e32 v52, v5
	v_add_f32_e32 v5, v47, v54
	v_sub_f32_e32 v53, v2, v3
	v_sub_f32_e32 v47, v2, v5
	v_mul_f32_e32 v53, 0x3fb8aa3b, v53
	v_mul_f32_e32 v47, 0x3fb8aa3b, v47
	v_exp_f32_e32 v53, v53
	v_exp_f32_e32 v47, v47
	v_pk_mul_f32 v[48:49], v[58:59], v[48:49]
	v_pk_mul_f32 v[52:53], v[0:1], v[52:53]
	v_pk_mul_f32 v[46:47], v[60:61], v[46:47]
	v_bfe_u32 v54, v53, 16, 1
	v_bfe_u32 v55, v52, 16, 1
	v_bfe_u32 v107, v49, 16, 1
	v_bfe_u32 v108, v48, 16, 1
	v_add3_u32 v52, v52, v55, s48
	v_add3_u32 v53, v53, v54, s48
	v_add3_u32 v54, v48, v108, s48
	v_add3_u32 v55, v49, v107, s48
	v_bfe_u32 v48, v46, 16, 1
	v_bfe_u32 v49, v47, 16, 1
	v_bfe_u32 v107, v50, 16, 1
	v_bfe_u32 v108, v51, 16, 1
	v_add3_u32 v47, v47, v49, s48
	v_add3_u32 v46, v46, v48, s48
	v_add3_u32 v48, v51, v108, s48
	v_add3_u32 v49, v50, v107, s48
	v_lshrrev_b32_e32 v46, 16, v46
	v_lshrrev_b32_e32 v47, 16, v47
	v_lshrrev_b32_e32 v50, 16, v49
	v_lshrrev_b32_e32 v51, 16, v48
	v_and_or_b32 v49, v53, s36, v47
	v_and_or_b32 v48, v52, s36, v46
	v_and_or_b32 v47, v55, s36, v51
	v_and_or_b32 v46, v54, s36, v50
	v_lshl_add_u64 v[50:51], v[38:39], 0, v[14:15]
	v_add_co_u32_e32 v50, vcc, 0x1000, v50
	s_nop 1
	v_addc_co_u32_e32 v51, vcc, 0, v51, vcc
	global_store_dwordx4 v[50:51], v[46:49], off
	s_and_saveexec_b64 s[30:31], s[8:9]
	s_cbranch_execz .LBB0_439
	v_mul_f32_e32 v2, 0x3fb8aa3b, v2
	v_exp_f32_e32 v2, v2
	v_lshl_add_u64 v[38:39], v[38:39], 0, v[8:9]
	v_add_co_u32_e32 v38, vcc, 0x2000, v38
	s_nop 1
	v_addc_co_u32_e32 v39, vcc, 0, v39, vcc
	global_store_dword v[38:39], v2, off offset:2048

.LBB0_665:
	s_mul_hi_i32 s12, s64, 0x2aaaaaab
	s_lshr_b32 s13, s12, 31
	s_ashr_i32 s12, s12, 2
	s_add_i32 s82, s12, s13
	s_mul_i32 s12, s82, 0xffffffe8
	s_add_i32 s92, s64, s12
	s_mov_b64 s[12:13], -1
	s_cmp_gt_i32 s92, 15
	v_lshl_add_u32 v103, s82, 5, v66
	s_cbranch_scc0 .LBB0_739
	v_mov_b32_e32 v155, v97
	s_add_i32 s12, s92, -16
	s_lshr_b32 s38, s12, 1
	s_and_b32 s28, s90, 2
	v_or_b32_e32 v146, s28, v62
	s_movk_i32 s26, 0x810
	v_cmp_gt_i32_e64 s[14:15], s26, v103
	s_mul_i32 s33, s38, 0x810
	s_nop 1
	v_cndmask_b32_e64 v140, 0, v103, s[14:15]
	v_add_u32_e32 v140, s33, v140
	v_mov_b64_e32 v[142:143], s[34:35]
	v_mad_i64_i32 v[144:145], s[16:17], v140, s44, v[142:143]
	v_lshl_or_b32 v140, v146, 7, v102
	v_or_b32_e32 v154, 0x2200, v140
	v_lshl_add_u64 v[146:147], v[144:145], 0, v[154:155]
	v_mov_b32_e32 v141, v155
	s_mov_b64 s[86:87], 0x2a00
	global_load_ushort v158, v[146:147], off
	v_lshl_add_u64 v[146:147], v[144:145], 0, v[140:141]
	v_lshl_add_u64 v[152:153], v[144:145], 0, s[86:87]
	v_add_co_u32_e32 v144, vcc, s74, v144
	s_nop 1
	v_addc_co_u32_e32 v145, vcc, 0, v145, vcc
	global_load_dwordx4 v[160:163], v[144:145], off offset:2560
	global_load_dwordx4 v[164:167], v[152:153], off offset:16
	v_or_b32_e32 v156, 2, v103
	v_cmp_gt_i32_e64 s[12:13], s26, v156
	v_or_b32_e32 v150, 3, v103
	v_or_b32_e32 v144, 1, v103
	v_cmp_gt_i32_e64 s[18:19], s26, v144
	v_cmp_gt_i32_e64 s[16:17], s26, v150
	s_nop 1
	v_cndmask_b32_e64 v144, 0, v144, s[18:19]
	v_add_u32_e32 v157, s33, v144
	v_mad_i64_i32 v[148:149], s[20:21], v157, s44, v[142:143]
	v_lshl_add_u64 v[144:145], v[148:149], 0, v[154:155]
	global_load_ushort v159, v[144:145], off
	v_lshl_add_u64 v[144:145], v[148:149], 0, v[140:141]
	v_lshl_add_u64 v[152:153], v[148:149], 0, s[86:87]
	v_add_co_u32_e32 v148, vcc, s74, v148
	s_nop 1
	v_addc_co_u32_e32 v149, vcc, 0, v149, vcc
	global_load_dwordx4 v[168:171], v[148:149], off offset:2560
	global_load_dwordx4 v[172:175], v[152:153], off offset:16
	v_cndmask_b32_e64 v148, 0, v156, s[12:13]
	v_add_u32_e32 v148, s33, v148
	v_mad_i64_i32 v[148:149], s[20:21], v148, s44, v[142:143]
	v_add_co_u32_e32 v146, vcc, s74, v146
	v_lshl_add_u64 v[152:153], v[148:149], 0, v[154:155]
	s_nop 1
	v_addc_co_u32_e32 v147, vcc, 0, v147, vcc
	global_load_ushort v176, v[152:153], off
	global_load_ushort v177, v[146:147], off offset:1024
	v_lshl_add_u64 v[152:153], v[148:149], 0, v[140:141]
	v_add_co_u32_e32 v146, vcc, s74, v152
	s_nop 1
	v_addc_co_u32_e32 v147, vcc, 0, v153, vcc
	global_load_ushort v178, v[146:147], off offset:1024
	v_lshl_add_u64 v[146:147], v[148:149], 0, s[86:87]
	v_add_co_u32_e32 v148, vcc, s74, v148
	s_nop 1
	v_addc_co_u32_e32 v149, vcc, 0, v149, vcc
	global_load_dwordx4 v[180:183], v[148:149], off offset:2560
	global_load_dwordx4 v[184:187], v[146:147], off offset:16
	v_cndmask_b32_e64 v146, 0, v150, s[16:17]
	v_add_u32_e32 v139, s33, v146
	v_mad_i64_i32 v[146:147], s[20:21], v139, s44, v[142:143]
	v_lshl_add_u64 v[150:151], v[146:147], 0, v[154:155]
	global_load_ushort v179, v[150:151], off
	v_lshl_add_u64 v[150:151], v[146:147], 0, v[140:141]
	v_add_co_u32_e32 v150, vcc, s74, v150
	s_nop 1
	v_addc_co_u32_e32 v151, vcc, 0, v151, vcc
	v_add_co_u32_e32 v144, vcc, s74, v144
	global_load_ushort v188, v[150:151], off offset:1024
	s_nop 1
	v_addc_co_u32_e32 v145, vcc, 0, v145, vcc
	global_load_ushort v189, v[144:145], off offset:1024
	v_lshl_add_u64 v[150:151], v[146:147], 0, s[86:87]
	v_add_co_u32_e32 v144, vcc, s74, v146
	s_nop 1
	v_addc_co_u32_e32 v145, vcc, 0, v147, vcc
	global_load_dwordx4 v[190:193], v[144:145], off offset:2560
	global_load_dwordx4 v[194:197], v[150:151], off offset:16
	s_add_i32 s12, s92, -16
	s_lshr_b32 s38, s12, 1
	s_and_b32 s28, s90, 2
	s_lshl_b32 s93, s38, 2
	v_or_b32_e32 v6, s28, v62
	s_add_i32 s93, s93, 32
	s_ashr_i32 s83, s82, 31
	v_or_b32_e32 v2, s93, v6
	v_mov_b64_e32 v[0:1], s[82:83]
	v_mad_u64_u32 v[0:1], s[12:13], v2, s79, v[0:1]
	v_mov_b64_e32 v[2:3], s[56:57]
	v_mad_u64_u32 v[38:39], s[12:13], v0, s44, v[2:3]
	v_lshlrev_b32_e32 v96, 8, v6
	v_mad_i32_i24 v39, v1, s44, v39
	v_lshl_add_u64 v[0:1], v[10:11], 0, v[96:97]
	global_load_dword v108, v[0:1], off
	v_lshl_add_u64 v[0:1], v[12:13], 0, v[96:97]
	s_movk_i32 s12, 0x1000
	v_add_co_u32_e32 v2, vcc, s12, v0
	global_load_dword v44, v[0:1], off
	global_load_dword v48, v[0:1], off offset:1024
	global_load_dword v42, v[0:1], off offset:2048
	global_load_dword v40, v[0:1], off offset:3072
	v_addc_co_u32_e32 v3, vcc, 0, v1, vcc
	v_add_co_u32_e32 v4, vcc, s74, v0
	s_movk_i32 s26, 0x810
	s_nop 0
	v_addc_co_u32_e32 v5, vcc, 0, v1, vcc
	v_add_co_u32_e32 v0, vcc, s44, v0
	v_cmp_gt_i32_e64 s[14:15], s26, v103
	s_nop 0
	v_addc_co_u32_e32 v1, vcc, 0, v1, vcc
	global_load_dword v54, v[4:5], off offset:-4096
	global_load_dword v52, v[2:3], off offset:1024
	global_load_dword v50, v[2:3], off offset:2048
	global_load_dword v46, v[2:3], off offset:3072
	global_load_dword v45, v[4:5], off
	global_load_dword v49, v[4:5], off offset:1024
	global_load_dword v43, v[4:5], off offset:2048
	global_load_dword v41, v[4:5], off offset:3072
	global_load_dword v55, v[0:1], off
	global_load_dword v53, v[0:1], off offset:1024
	global_load_dword v51, v[0:1], off offset:2048
	global_load_dword v47, v[0:1], off offset:3072
	s_mul_i32 s33, s38, 0x810
	v_cndmask_b32_e64 v0, 0, v103, s[14:15]
	v_add_u32_e32 v0, s33, v0
	v_mov_b64_e32 v[2:3], s[34:35]
	v_mad_i64_i32 v[4:5], s[16:17], v0, s44, v[2:3]
	v_lshl_or_b32 v0, v6, 7, v102
	v_or_b32_e32 v96, 0x2200, v0
	v_lshl_add_u64 v[6:7], v[4:5], 0, v[96:97]
	v_mov_b32_e32 v1, v97
	s_mov_b64 s[86:87], 0x2a00
	s_waitcnt vmcnt(0)
	v_mov_b32_e32 v107, v158
	v_lshl_add_u64 v[6:7], v[4:5], 0, v[0:1]
	v_lshl_add_u64 v[60:61], v[4:5], 0, s[86:87]
	v_add_co_u32_e32 v4, vcc, s74, v4
	s_mov_b32 s29, 0x3f317217
	s_nop 0
	v_addc_co_u32_e32 v5, vcc, 0, v5, vcc
	v_mov_b64_e32 v[56:57], v[160:161]
	v_mov_b64_e32 v[58:59], v[162:163]
	v_mov_b64_e32 v[110:111], v[164:165]
	v_mov_b64_e32 v[112:113], v[166:167]
	v_mov_b32_e32 v138, 0x41b17218
	v_or_b32_e32 v104, 2, v103
	v_cmp_gt_i32_e64 s[12:13], s26, v104
	s_waitcnt vmcnt(0)
	v_and_b32_e32 v60, 0xffff0000, v56
	v_and_b32_e32 v61, 0xffff0000, v110
	v_lshlrev_b32_e32 v4, 16, v56
	v_lshlrev_b32_e32 v5, 16, v110
	v_pk_mul_f32 v[60:61], v[48:49], v[60:61]
	v_lshlrev_b32_e32 v56, 16, v58
	v_pk_fma_f32 v[4:5], v[44:45], v[4:5], v[60:61]
	v_lshlrev_b32_e32 v60, 16, v57
	v_lshlrev_b32_e32 v61, 16, v111
	v_pk_fma_f32 v[4:5], v[42:43], v[60:61], v[4:5]
	v_and_b32_e32 v61, 0xffff0000, v111
	v_and_b32_e32 v60, 0xffff0000, v57
	v_pk_fma_f32 v[4:5], v[40:41], v[60:61], v[4:5]
	v_lshlrev_b32_e32 v57, 16, v112
	v_pk_fma_f32 v[4:5], v[54:55], v[56:57], v[4:5]
	v_and_b32_e32 v57, 0xffff0000, v112
	v_and_b32_e32 v56, 0xffff0000, v58
	v_pk_fma_f32 v[4:5], v[52:53], v[56:57], v[4:5]
	v_lshlrev_b32_e32 v56, 16, v59
	v_lshlrev_b32_e32 v57, 16, v113
	v_pk_fma_f32 v[4:5], v[50:51], v[56:57], v[4:5]
	v_and_b32_e32 v57, 0xffff0000, v113
	v_and_b32_e32 v56, 0xffff0000, v59
	v_pk_fma_f32 v[4:5], v[46:47], v[56:57], v[4:5]
	v_or_b32_e32 v58, 3, v103
	v_add_f32_e32 v4, v108, v4
	v_add_f32_e32 v4, v4, v5
	v_min_f32_e32 v5, 0, v4
	v_mul_f32_e64 v4, |v4|, s94
	v_exp_f32_e32 v4, v4
	s_nop 0
	v_add_f32_e32 v4, 1.0, v4
	v_cmp_gt_f32_e32 vcc, s45, v4
	s_nop 1
	v_cndmask_b32_e64 v56, 0, 32, vcc
	v_ldexp_f32 v4, v4, v56
	v_log_f32_e32 v4, v4
	s_nop 0
	v_mul_f32_e32 v56, 0x3f317217, v4
	v_fma_f32 v56, v4, s29, -v56
	v_fmac_f32_e32 v56, 0x3377d1cf, v4
	v_fmac_f32_e32 v56, 0x3f317217, v4
	v_cmp_lt_f32_e64 s[16:17], |v4|, s95
	s_nop 1
	v_cndmask_b32_e64 v4, v4, v56, s[16:17]
	v_cndmask_b32_e32 v56, 0, v138, vcc
	v_sub_f32_e32 v4, v4, v56
	v_sub_f32_e32 v4, v5, v4
	s_mov_b32 s16, 0x3d800000
	v_fma_f32 v4, v4, s16, 0
	v_cndmask_b32_e64 v109, 0, v4, s[14:15]
	v_or_b32_e32 v4, 1, v103
	v_cmp_gt_i32_e64 s[18:19], s26, v4
	v_cmp_gt_i32_e64 s[16:17], s26, v58
	s_nop 0
	v_cndmask_b32_e64 v4, 0, v4, s[18:19]
	v_add_u32_e32 v105, s33, v4
	v_mad_i64_i32 v[56:57], s[20:21], v105, s44, v[2:3]
	v_lshl_add_u64 v[4:5], v[56:57], 0, v[96:97]
	v_mov_b32_e32 v110, v159
	v_lshl_add_u64 v[4:5], v[56:57], 0, v[0:1]
	v_lshl_add_u64 v[60:61], v[56:57], 0, s[86:87]
	v_add_co_u32_e32 v56, vcc, s74, v56
	s_nop 1
	v_addc_co_u32_e32 v57, vcc, 0, v57, vcc
	v_mov_b64_e32 v[112:113], v[168:169]
	v_mov_b64_e32 v[114:115], v[170:171]
	v_mov_b64_e32 v[116:117], v[172:173]
	v_mov_b64_e32 v[118:119], v[174:175]
	s_waitcnt vmcnt(0)
	v_and_b32_e32 v60, 0xffff0000, v112
	s_waitcnt vmcnt(0)
	v_and_b32_e32 v61, 0xffff0000, v116
	v_lshlrev_b32_e32 v56, 16, v112
	v_lshlrev_b32_e32 v57, 16, v116
	v_pk_mul_f32 v[60:61], v[48:49], v[60:61]
	s_nop 0
	v_pk_fma_f32 v[56:57], v[44:45], v[56:57], v[60:61]
	v_lshlrev_b32_e32 v60, 16, v113
	v_lshlrev_b32_e32 v61, 16, v117
	v_pk_fma_f32 v[56:57], v[42:43], v[60:61], v[56:57]
	v_and_b32_e32 v61, 0xffff0000, v117
	v_and_b32_e32 v60, 0xffff0000, v113
	v_pk_fma_f32 v[56:57], v[40:41], v[60:61], v[56:57]
	v_lshlrev_b32_e32 v60, 16, v114
	v_lshlrev_b32_e32 v61, 16, v118
	v_pk_fma_f32 v[56:57], v[54:55], v[60:61], v[56:57]
	v_and_b32_e32 v61, 0xffff0000, v118
	v_and_b32_e32 v60, 0xffff0000, v114
	v_pk_fma_f32 v[56:57], v[52:53], v[60:61], v[56:57]
	v_lshlrev_b32_e32 v60, 16, v115
	v_lshlrev_b32_e32 v61, 16, v119
	v_pk_fma_f32 v[56:57], v[50:51], v[60:61], v[56:57]
	v_and_b32_e32 v61, 0xffff0000, v119
	v_and_b32_e32 v60, 0xffff0000, v115
	v_pk_fma_f32 v[56:57], v[46:47], v[60:61], v[56:57]
	s_nop 0
	v_add_f32_e32 v56, v108, v56
	v_add_f32_e32 v56, v56, v57
	v_min_f32_e32 v57, 0, v56
	v_mul_f32_e64 v56, |v56|, s94
	v_exp_f32_e32 v56, v56
	s_nop 0
	v_add_f32_e32 v56, 1.0, v56
	v_cmp_gt_f32_e32 vcc, s45, v56
	s_nop 1
	v_cndmask_b32_e64 v59, 0, 32, vcc
	v_ldexp_f32 v56, v56, v59
	v_log_f32_e32 v56, v56
	s_nop 0
	v_mul_f32_e32 v59, 0x3f317217, v56
	v_fma_f32 v59, v56, s29, -v59
	v_fmac_f32_e32 v59, 0x3377d1cf, v56
	v_fmac_f32_e32 v59, 0x3f317217, v56
	v_cmp_lt_f32_e64 s[20:21], |v56|, s95
	s_nop 1
	v_cndmask_b32_e64 v56, v56, v59, s[20:21]
	v_cndmask_b32_e32 v59, 0, v138, vcc
	v_sub_f32_e32 v56, v56, v59
	v_sub_f32_e32 v56, v57, v56
	v_mul_f32_e32 v56, 0x3d800000, v56
	v_cndmask_b32_e64 v56, 0, v56, s[18:19]
	v_add_f32_e32 v113, v109, v56
	v_cndmask_b32_e64 v56, 0, v104, s[12:13]
	v_add_u32_e32 v56, s33, v56
	v_mad_i64_i32 v[56:57], s[20:21], v56, s44, v[2:3]
	v_add_co_u32_e32 v6, vcc, s74, v6
	v_lshl_add_u64 v[60:61], v[56:57], 0, v[96:97]
	s_nop 0
	v_addc_co_u32_e32 v7, vcc, 0, v7, vcc
	v_mov_b32_e32 v114, v176
	v_mov_b32_e32 v59, v177
	v_lshl_add_u64 v[60:61], v[56:57], 0, v[0:1]
	v_add_co_u32_e32 v6, vcc, s74, v60
	s_waitcnt vmcnt(0)
	v_lshlrev_b32_e32 v59, 16, v59
	v_addc_co_u32_e32 v7, vcc, 0, v61, vcc
	v_mov_b32_e32 v6, v178
	s_waitcnt vmcnt(0)
	v_lshlrev_b32_e32 v60, 16, v6
	v_lshl_add_u64 v[6:7], v[56:57], 0, s[86:87]
	v_add_co_u32_e32 v56, vcc, s74, v56
	s_nop 1
	v_addc_co_u32_e32 v57, vcc, 0, v57, vcc
	v_mov_b64_e32 v[116:117], v[180:181]
	v_mov_b64_e32 v[118:119], v[182:183]
	v_mov_b64_e32 v[120:121], v[184:185]
	v_mov_b64_e32 v[122:123], v[186:187]
	s_waitcnt vmcnt(0)
	v_and_b32_e32 v56, 0xffff0000, v116
	s_waitcnt vmcnt(0)
	v_and_b32_e32 v57, 0xffff0000, v120
	v_lshlrev_b32_e32 v6, 16, v116
	v_lshlrev_b32_e32 v7, 16, v120
	v_pk_mul_f32 v[56:57], v[48:49], v[56:57]
	s_nop 0
	v_pk_fma_f32 v[6:7], v[44:45], v[6:7], v[56:57]
	v_lshlrev_b32_e32 v56, 16, v117
	v_lshlrev_b32_e32 v57, 16, v121
	v_pk_fma_f32 v[6:7], v[42:43], v[56:57], v[6:7]
	v_and_b32_e32 v57, 0xffff0000, v121
	v_and_b32_e32 v56, 0xffff0000, v117
	v_pk_fma_f32 v[6:7], v[40:41], v[56:57], v[6:7]
	v_lshlrev_b32_e32 v56, 16, v118
	v_lshlrev_b32_e32 v57, 16, v122
	v_pk_fma_f32 v[6:7], v[54:55], v[56:57], v[6:7]
	v_and_b32_e32 v57, 0xffff0000, v122
	v_and_b32_e32 v56, 0xffff0000, v118
	v_pk_fma_f32 v[6:7], v[52:53], v[56:57], v[6:7]
	v_lshlrev_b32_e32 v56, 16, v119
	v_lshlrev_b32_e32 v57, 16, v123
	v_pk_fma_f32 v[6:7], v[50:51], v[56:57], v[6:7]
	v_and_b32_e32 v57, 0xffff0000, v123
	v_and_b32_e32 v56, 0xffff0000, v119
	v_pk_fma_f32 v[6:7], v[46:47], v[56:57], v[6:7]
	v_cndmask_b32_e64 v57, 0, v60, s[12:13]
	v_add_f32_e32 v6, v108, v6
	v_add_f32_e32 v6, v6, v7
	v_min_f32_e32 v7, 0, v6
	v_mul_f32_e64 v6, |v6|, s94
	v_exp_f32_e32 v6, v6
	s_nop 0
	v_add_f32_e32 v6, 1.0, v6
	v_cmp_gt_f32_e32 vcc, s45, v6
	s_nop 1
	v_cndmask_b32_e64 v56, 0, 32, vcc
	v_ldexp_f32 v6, v6, v56
	v_log_f32_e32 v6, v6
	s_nop 0
	v_mul_f32_e32 v56, 0x3f317217, v6
	v_fma_f32 v56, v6, s29, -v56
	v_fmac_f32_e32 v56, 0x3377d1cf, v6
	v_fmac_f32_e32 v56, 0x3f317217, v6
	v_cmp_lt_f32_e64 s[20:21], |v6|, s95
	s_nop 1
	v_cndmask_b32_e64 v6, v6, v56, s[20:21]
	v_cndmask_b32_e32 v56, 0, v138, vcc
	v_sub_f32_e32 v6, v6, v56
	v_sub_f32_e32 v6, v7, v6
	v_mul_f32_e32 v6, 0x3d800000, v6
	v_cndmask_b32_e64 v6, 0, v6, s[12:13]
	v_add_f32_e32 v117, v113, v6
	v_cndmask_b32_e64 v6, 0, v58, s[16:17]
	v_add_u32_e32 v111, s33, v6
	v_mad_i64_i32 v[6:7], s[20:21], v111, s44, v[2:3]
	v_cndmask_b32_e64 v56, 0, v59, s[14:15]
	v_lshl_add_u64 v[58:59], v[6:7], 0, v[96:97]
	v_mov_b32_e32 v116, v179
	v_lshl_add_u64 v[58:59], v[6:7], 0, v[0:1]
	v_add_co_u32_e32 v58, vcc, s74, v58
	s_nop 1
	v_addc_co_u32_e32 v59, vcc, 0, v59, vcc
	v_add_co_u32_e32 v4, vcc, s74, v4
	v_mov_b32_e32 v58, v188
	s_nop 0
	v_addc_co_u32_e32 v5, vcc, 0, v5, vcc
	v_mov_b32_e32 v4, v189
	s_waitcnt vmcnt(0)
	v_lshlrev_b32_e32 v115, 16, v58
	v_lshl_add_u64 v[58:59], v[6:7], 0, s[86:87]
	s_waitcnt vmcnt(0)
	v_lshlrev_b32_e32 v112, 16, v4
	v_add_co_u32_e32 v4, vcc, s74, v6
	s_nop 1
	v_addc_co_u32_e32 v5, vcc, 0, v7, vcc
	v_mov_b64_e32 v[4:5], v[190:191]
	v_mov_b64_e32 v[6:7], v[192:193]
	s_nop 0
	v_mov_b64_e32 v[58:59], v[194:195]
	v_mov_b64_e32 v[60:61], v[196:197]
	v_mov_b32_e32 v142, v2
	v_mov_b32_e32 v143, v3
	v_mov_b32_e32 v140, v0
	v_mov_b32_e32 v141, v1
	v_or_b32_e32 v139, 4, v103
	v_cmp_gt_i32_e64 s[22:23], s26, v139
	v_or_b32_e32 v150, 6, v103
	s_nop 1
	v_cndmask_b32_e64 v144, 0, v139, s[22:23]
	v_add_u32_e32 v144, s33, v144
	v_mad_i64_i32 v[146:147], s[24:25], v144, s44, v[142:143]
	v_lshl_add_u64 v[144:145], v[146:147], 0, v[96:97]
	global_load_ushort v151, v[144:145], off
	v_lshl_add_u64 v[144:145], v[146:147], 0, v[140:141]
	v_lshl_add_u64 v[148:149], v[146:147], 0, s[86:87]
	v_add_co_u32_e32 v146, vcc, s74, v146
	v_cmp_gt_i32_e64 s[20:21], s26, v150
	s_nop 1
	v_addc_co_u32_e32 v147, vcc, 0, v147, vcc
	global_load_dwordx4 v[160:163], v[146:147], off offset:2560
	global_load_dwordx4 v[164:167], v[148:149], off offset:16
	v_or_b32_e32 v154, 7, v103
	v_or_b32_e32 v146, 5, v103
	v_cmp_gt_i32_e64 s[24:25], s26, v154
	v_cmp_gt_i32_e64 s[98:99], s26, v146
	s_nop 1
	v_cndmask_b32_e64 v146, 0, v146, s[98:99]
	v_add_u32_e32 v152, s33, v146
	v_mad_i64_i32 v[148:149], s[30:31], v152, s44, v[142:143]
	v_lshl_add_u64 v[146:147], v[148:149], 0, v[96:97]
	global_load_ushort v153, v[146:147], off
	v_lshl_add_u64 v[146:147], v[148:149], 0, v[140:141]
	v_lshl_add_u64 v[158:159], v[148:149], 0, s[86:87]
	v_add_co_u32_e32 v148, vcc, s74, v148
	s_nop 1
	v_addc_co_u32_e32 v149, vcc, 0, v149, vcc
	global_load_dwordx4 v[168:171], v[148:149], off offset:2560
	global_load_dwordx4 v[172:175], v[158:159], off offset:16
	v_cndmask_b32_e64 v148, 0, v150, s[20:21]
	v_add_u32_e32 v148, s33, v148
	v_mad_i64_i32 v[148:149], s[30:31], v148, s44, v[142:143]
	v_lshl_add_u64 v[156:157], v[148:149], 0, v[96:97]
	global_load_ushort v155, v[156:157], off
	v_lshl_add_u64 v[156:157], v[148:149], 0, v[140:141]
	v_add_co_u32_e32 v156, vcc, s74, v156
	s_nop 1
	v_addc_co_u32_e32 v157, vcc, 0, v157, vcc
	v_add_co_u32_e32 v144, vcc, s74, v144
	global_load_ushort v176, v[156:157], off offset:1024
	s_nop 1
	v_addc_co_u32_e32 v145, vcc, 0, v145, vcc
	global_load_ushort v177, v[144:145], off offset:1024
	v_lshl_add_u64 v[144:145], v[148:149], 0, s[86:87]
	v_add_co_u32_e32 v148, vcc, s74, v148
	s_nop 1
	v_addc_co_u32_e32 v149, vcc, 0, v149, vcc
	global_load_dwordx4 v[178:181], v[148:149], off offset:2560
	global_load_dwordx4 v[182:185], v[144:145], off offset:16
	v_cndmask_b32_e64 v144, 0, v154, s[24:25]
	v_add_u32_e32 v154, s33, v144
	v_mad_i64_i32 v[142:143], s[30:31], v154, s44, v[142:143]
	v_lshl_add_u64 v[140:141], v[142:143], 0, v[140:141]
	v_add_co_u32_e32 v140, vcc, s74, v140
	v_lshl_add_u64 v[144:145], v[142:143], 0, v[96:97]
	s_nop 1
	v_addc_co_u32_e32 v141, vcc, 0, v141, vcc
	global_load_ushort v186, v[144:145], off
	global_load_ushort v187, v[140:141], off offset:1024
	v_add_co_u32_e32 v140, vcc, s74, v146
	s_nop 1
	v_addc_co_u32_e32 v141, vcc, 0, v147, vcc
	global_load_ushort v188, v[140:141], off offset:1024
	v_lshl_add_u64 v[144:145], v[142:143], 0, s[86:87]
	v_add_co_u32_e32 v140, vcc, s74, v142
	s_nop 1
	v_addc_co_u32_e32 v141, vcc, 0, v143, vcc
	global_load_dwordx4 v[190:193], v[140:141], off offset:2560
	global_load_dwordx4 v[194:197], v[144:145], off offset:16
	s_waitcnt vmcnt(0)
	v_and_b32_e32 v120, 0xffff0000, v4
	s_waitcnt vmcnt(0)
	v_and_b32_e32 v121, 0xffff0000, v58
	v_lshlrev_b32_e32 v118, 16, v4
	v_lshlrev_b32_e32 v119, 16, v58
	v_pk_mul_f32 v[120:121], v[48:49], v[120:121]
	v_and_b32_e32 v58, 0xffff0000, v5
	v_pk_fma_f32 v[118:119], v[44:45], v[118:119], v[120:121]
	v_lshlrev_b32_e32 v120, 16, v5
	v_lshlrev_b32_e32 v121, 16, v59
	v_pk_fma_f32 v[118:119], v[42:43], v[120:121], v[118:119]
	v_and_b32_e32 v59, 0xffff0000, v59
	v_pk_fma_f32 v[4:5], v[40:41], v[58:59], v[118:119]
	v_lshlrev_b32_e32 v58, 16, v6
	v_lshlrev_b32_e32 v59, 16, v60
	v_pk_fma_f32 v[4:5], v[54:55], v[58:59], v[4:5]
	v_and_b32_e32 v59, 0xffff0000, v60
	v_and_b32_e32 v58, 0xffff0000, v6
	v_pk_fma_f32 v[4:5], v[52:53], v[58:59], v[4:5]
	v_lshlrev_b32_e32 v58, 16, v7
	v_lshlrev_b32_e32 v59, 16, v61
	v_pk_fma_f32 v[4:5], v[50:51], v[58:59], v[4:5]
	v_and_b32_e32 v59, 0xffff0000, v61
	v_and_b32_e32 v58, 0xffff0000, v7
	v_pk_fma_f32 v[4:5], v[46:47], v[58:59], v[4:5]
	v_cndmask_b32_e64 v59, 0, v115, s[16:17]
	v_add_f32_e32 v4, v108, v4
	v_add_f32_e32 v4, v4, v5
	v_min_f32_e32 v5, 0, v4
	v_mul_f32_e64 v4, |v4|, s94
	v_exp_f32_e32 v4, v4
	v_or_b32_e32 v115, 4, v103
	v_cmp_gt_i32_e64 s[22:23], s26, v115
	v_cndmask_b32_e64 v58, 0, v112, s[18:19]
	v_add_f32_e32 v4, 1.0, v4
	v_cmp_gt_f32_e32 vcc, s45, v4
	v_or_b32_e32 v112, 6, v103
	s_nop 0
	v_cndmask_b32_e64 v6, 0, 32, vcc
	v_ldexp_f32 v4, v4, v6
	v_log_f32_e32 v4, v4
	s_nop 0
	v_mul_f32_e32 v6, 0x3f317217, v4
	v_fma_f32 v6, v4, s29, -v6
	v_fmac_f32_e32 v6, 0x3377d1cf, v4
	v_fmac_f32_e32 v6, 0x3f317217, v4
	v_cmp_lt_f32_e64 s[20:21], |v4|, s95
	s_nop 1
	v_cndmask_b32_e64 v4, v4, v6, s[20:21]
	v_cndmask_b32_e32 v6, 0, v138, vcc
	v_sub_f32_e32 v4, v4, v6
	v_sub_f32_e32 v4, v5, v4
	v_mul_f32_e32 v4, 0x3d800000, v4
	v_cndmask_b32_e64 v4, 0, v4, s[16:17]
	v_add_f32_e32 v120, v117, v4
	v_cndmask_b32_e64 v4, 0, v115, s[22:23]
	v_add_u32_e32 v4, s33, v4
	v_mad_i64_i32 v[6:7], s[24:25], v4, s44, v[2:3]
	v_lshl_add_u64 v[4:5], v[6:7], 0, v[96:97]
	s_waitcnt vmcnt(0)
	v_mov_b32_e32 v119, v151
	v_lshl_add_u64 v[4:5], v[6:7], 0, v[0:1]
	v_lshl_add_u64 v[60:61], v[6:7], 0, s[86:87]
	v_add_co_u32_e32 v6, vcc, s74, v6
	v_cmp_gt_i32_e64 s[20:21], s26, v112
	s_nop 0
	v_addc_co_u32_e32 v7, vcc, 0, v7, vcc
	v_mov_b64_e32 v[122:123], v[160:161]
	v_mov_b64_e32 v[124:125], v[162:163]
	v_mov_b64_e32 v[126:127], v[164:165]
	v_mov_b64_e32 v[128:129], v[166:167]
	s_waitcnt vmcnt(0)
	v_and_b32_e32 v60, 0xffff0000, v122
	s_waitcnt vmcnt(0)
	v_and_b32_e32 v61, 0xffff0000, v126
	v_lshlrev_b32_e32 v6, 16, v122
	v_lshlrev_b32_e32 v7, 16, v126
	v_pk_mul_f32 v[60:61], v[48:49], v[60:61]
	s_nop 0
	v_pk_fma_f32 v[6:7], v[44:45], v[6:7], v[60:61]
	v_lshlrev_b32_e32 v60, 16, v123
	v_lshlrev_b32_e32 v61, 16, v127
	v_pk_fma_f32 v[6:7], v[42:43], v[60:61], v[6:7]
	v_and_b32_e32 v61, 0xffff0000, v127
	v_and_b32_e32 v60, 0xffff0000, v123
	v_pk_fma_f32 v[6:7], v[40:41], v[60:61], v[6:7]
	v_lshlrev_b32_e32 v60, 16, v124
	v_lshlrev_b32_e32 v61, 16, v128
	v_pk_fma_f32 v[6:7], v[54:55], v[60:61], v[6:7]
	v_and_b32_e32 v61, 0xffff0000, v128
	v_and_b32_e32 v60, 0xffff0000, v124
	v_pk_fma_f32 v[6:7], v[52:53], v[60:61], v[6:7]
	v_lshlrev_b32_e32 v60, 16, v125
	v_lshlrev_b32_e32 v61, 16, v129
	v_pk_fma_f32 v[6:7], v[50:51], v[60:61], v[6:7]
	v_and_b32_e32 v61, 0xffff0000, v129
	v_and_b32_e32 v60, 0xffff0000, v125
	v_pk_fma_f32 v[6:7], v[46:47], v[60:61], v[6:7]
	v_or_b32_e32 v124, 7, v103
	v_add_f32_e32 v6, v108, v6
	v_add_f32_e32 v6, v6, v7
	v_min_f32_e32 v7, 0, v6
	v_mul_f32_e64 v6, |v6|, s94
	v_exp_f32_e32 v6, v6
	s_nop 0
	v_add_f32_e32 v6, 1.0, v6
	v_cmp_gt_f32_e32 vcc, s45, v6
	s_nop 1
	v_cndmask_b32_e64 v60, 0, 32, vcc
	v_ldexp_f32 v6, v6, v60
	v_log_f32_e32 v6, v6
	s_nop 0
	v_mul_f32_e32 v60, 0x3f317217, v6
	v_fma_f32 v60, v6, s29, -v60
	v_fmac_f32_e32 v60, 0x3377d1cf, v6
	v_fmac_f32_e32 v60, 0x3f317217, v6
	v_cmp_lt_f32_e64 s[24:25], |v6|, s95
	s_nop 1
	v_cndmask_b32_e64 v6, v6, v60, s[24:25]
	v_cndmask_b32_e32 v60, 0, v138, vcc
	v_sub_f32_e32 v6, v6, v60
	v_sub_f32_e32 v6, v7, v6
	v_mul_f32_e32 v6, 0x3d800000, v6
	v_cndmask_b32_e64 v123, 0, v6, s[22:23]
	v_or_b32_e32 v6, 5, v103
	v_cmp_gt_i32_e64 s[24:25], s26, v124
	v_cmp_gt_i32_e64 s[26:27], s26, v6
	s_nop 1
	v_cndmask_b32_e64 v6, 0, v6, s[26:27]
	v_add_u32_e32 v118, s33, v6
	v_mad_i64_i32 v[60:61], s[30:31], v118, s44, v[2:3]
	v_lshl_add_u64 v[6:7], v[60:61], 0, v[96:97]
	v_mov_b32_e32 v121, v153
	v_lshl_add_u64 v[6:7], v[60:61], 0, v[0:1]
	v_lshl_add_u64 v[130:131], v[60:61], 0, s[86:87]
	v_add_co_u32_e32 v60, vcc, s74, v60
	s_nop 1
	v_addc_co_u32_e32 v61, vcc, 0, v61, vcc
	v_mov_b64_e32 v[126:127], v[168:169]
	v_mov_b64_e32 v[128:129], v[170:171]
	s_nop 0
	v_mov_b64_e32 v[130:131], v[172:173]
	v_mov_b64_e32 v[132:133], v[174:175]
	s_waitcnt vmcnt(0)
	v_and_b32_e32 v134, 0xffff0000, v126
	s_waitcnt vmcnt(0)
	v_and_b32_e32 v135, 0xffff0000, v130
	v_lshlrev_b32_e32 v60, 16, v126
	v_lshlrev_b32_e32 v61, 16, v130
	v_pk_mul_f32 v[134:135], v[48:49], v[134:135]
	v_and_b32_e32 v130, 0xffff0000, v127
	v_pk_fma_f32 v[60:61], v[44:45], v[60:61], v[134:135]
	v_lshlrev_b32_e32 v134, 16, v127
	v_lshlrev_b32_e32 v135, 16, v131
	v_pk_fma_f32 v[60:61], v[42:43], v[134:135], v[60:61]
	v_and_b32_e32 v131, 0xffff0000, v131
	v_pk_fma_f32 v[60:61], v[40:41], v[130:131], v[60:61]
	v_lshlrev_b32_e32 v126, 16, v128
	v_lshlrev_b32_e32 v127, 16, v132
	v_pk_fma_f32 v[60:61], v[54:55], v[126:127], v[60:61]
	v_and_b32_e32 v127, 0xffff0000, v132
	v_and_b32_e32 v126, 0xffff0000, v128
	v_pk_fma_f32 v[60:61], v[52:53], v[126:127], v[60:61]
	v_lshlrev_b32_e32 v126, 16, v129
	v_lshlrev_b32_e32 v127, 16, v133
	v_pk_fma_f32 v[60:61], v[50:51], v[126:127], v[60:61]
	v_and_b32_e32 v127, 0xffff0000, v133
	v_and_b32_e32 v126, 0xffff0000, v129
	v_pk_fma_f32 v[60:61], v[46:47], v[126:127], v[60:61]
	s_nop 0
	v_add_f32_e32 v60, v108, v60
	v_add_f32_e32 v60, v60, v61
	v_min_f32_e32 v61, 0, v60
	v_mul_f32_e64 v60, |v60|, s94
	v_exp_f32_e32 v60, v60
	s_nop 0
	v_add_f32_e32 v60, 1.0, v60
	v_cmp_gt_f32_e32 vcc, s45, v60
	s_nop 1
	v_cndmask_b32_e64 v122, 0, 32, vcc
	v_ldexp_f32 v60, v60, v122
	v_log_f32_e32 v60, v60
	s_nop 0
	v_mul_f32_e32 v122, 0x3f317217, v60
	v_fma_f32 v122, v60, s29, -v122
	v_fmac_f32_e32 v122, 0x3377d1cf, v60
	v_fmac_f32_e32 v122, 0x3f317217, v60
	v_cmp_lt_f32_e64 s[30:31], |v60|, s95
	s_nop 1
	v_cndmask_b32_e64 v60, v60, v122, s[30:31]
	v_cndmask_b32_e32 v122, 0, v138, vcc
	v_sub_f32_e32 v60, v60, v122
	v_sub_f32_e32 v60, v61, v60
	v_mul_f32_e32 v60, 0x3d800000, v60
	v_cndmask_b32_e64 v125, 0, v60, s[26:27]
	v_cndmask_b32_e64 v60, 0, v112, s[20:21]
	v_add_u32_e32 v60, s33, v60
	v_mad_i64_i32 v[60:61], s[30:31], v60, s44, v[2:3]
	v_lshl_add_u64 v[126:127], v[60:61], 0, v[96:97]
	v_mov_b32_e32 v122, v155
	v_lshl_add_u64 v[126:127], v[60:61], 0, v[0:1]
	v_add_co_u32_e32 v126, vcc, s74, v126
	s_nop 1
	v_addc_co_u32_e32 v127, vcc, 0, v127, vcc
	v_add_co_u32_e32 v4, vcc, s74, v4
	v_mov_b32_e32 v126, v176
	s_nop 0
	v_addc_co_u32_e32 v5, vcc, 0, v5, vcc
	v_mov_b32_e32 v4, v177
	s_waitcnt vmcnt(0)
	v_lshlrev_b32_e32 v135, 16, v126
	s_waitcnt vmcnt(0)
	v_lshlrev_b32_e32 v134, 16, v4
	v_lshl_add_u64 v[4:5], v[60:61], 0, s[86:87]
	v_add_co_u32_e32 v60, vcc, s74, v60
	s_nop 1
	v_addc_co_u32_e32 v61, vcc, 0, v61, vcc
	v_mov_b64_e32 v[126:127], v[178:179]
	v_mov_b64_e32 v[128:129], v[180:181]
	v_mov_b64_e32 v[130:131], v[182:183]
	v_mov_b64_e32 v[132:133], v[184:185]
	s_waitcnt vmcnt(0)
	v_and_b32_e32 v60, 0xffff0000, v126
	s_waitcnt vmcnt(0)
	v_and_b32_e32 v61, 0xffff0000, v130
	v_lshlrev_b32_e32 v4, 16, v126
	v_lshlrev_b32_e32 v5, 16, v130
	v_pk_mul_f32 v[60:61], v[48:49], v[60:61]
	s_nop 0
	v_pk_fma_f32 v[4:5], v[44:45], v[4:5], v[60:61]
	v_lshlrev_b32_e32 v60, 16, v127
	v_lshlrev_b32_e32 v61, 16, v131
	v_pk_fma_f32 v[4:5], v[42:43], v[60:61], v[4:5]
	v_and_b32_e32 v61, 0xffff0000, v131
	v_and_b32_e32 v60, 0xffff0000, v127
	v_pk_fma_f32 v[4:5], v[40:41], v[60:61], v[4:5]
	v_lshlrev_b32_e32 v60, 16, v128
	v_lshlrev_b32_e32 v61, 16, v132
	v_pk_fma_f32 v[4:5], v[54:55], v[60:61], v[4:5]
	v_and_b32_e32 v61, 0xffff0000, v132
	v_and_b32_e32 v60, 0xffff0000, v128
	v_pk_fma_f32 v[4:5], v[52:53], v[60:61], v[4:5]
	v_lshlrev_b32_e32 v60, 16, v129
	v_lshlrev_b32_e32 v61, 16, v133
	v_pk_fma_f32 v[4:5], v[50:51], v[60:61], v[4:5]
	v_and_b32_e32 v61, 0xffff0000, v133
	v_and_b32_e32 v60, 0xffff0000, v129
	v_pk_fma_f32 v[4:5], v[46:47], v[60:61], v[4:5]
	v_cndmask_b32_e64 v61, 0, v135, s[20:21]
	v_add_f32_e32 v4, v108, v4
	v_add_f32_e32 v4, v4, v5
	v_min_f32_e32 v5, 0, v4
	v_mul_f32_e64 v4, |v4|, s94
	v_exp_f32_e32 v4, v4
	s_nop 0
	v_add_f32_e32 v4, 1.0, v4
	v_cmp_gt_f32_e32 vcc, s45, v4
	s_nop 1
	v_cndmask_b32_e64 v60, 0, 32, vcc
	v_ldexp_f32 v4, v4, v60
	v_log_f32_e32 v4, v4
	s_nop 0
	v_mul_f32_e32 v60, 0x3f317217, v4
	v_fma_f32 v60, v4, s29, -v60
	v_fmac_f32_e32 v60, 0x3377d1cf, v4
	v_fmac_f32_e32 v60, 0x3f317217, v4
	v_cmp_lt_f32_e64 s[30:31], |v4|, s95
	s_nop 1
	v_cndmask_b32_e64 v4, v4, v60, s[30:31]
	v_cndmask_b32_e32 v60, 0, v138, vcc
	v_sub_f32_e32 v4, v4, v60
	v_sub_f32_e32 v4, v5, v4
	v_mul_f32_e32 v4, 0x3d800000, v4
	v_cndmask_b32_e64 v126, 0, v4, s[20:21]
	v_cndmask_b32_e64 v4, 0, v124, s[24:25]
	v_add_u32_e32 v124, s33, v4
	v_mad_i64_i32 v[2:3], s[30:31], v124, s44, v[2:3]
	v_lshl_add_u64 v[0:1], v[2:3], 0, v[0:1]
	v_add_co_u32_e32 v0, vcc, s74, v0
	v_lshl_add_u64 v[4:5], v[2:3], 0, v[96:97]
	s_nop 0
	v_addc_co_u32_e32 v1, vcc, 0, v1, vcc
	v_mov_b32_e32 v96, v186
	v_cndmask_b32_e64 v60, 0, v134, s[22:23]
	v_mov_b32_e32 v4, v187
	v_add_co_u32_e32 v0, vcc, s74, v6
	s_waitcnt vmcnt(0)
	v_lshlrev_b32_e32 v132, 16, v4
	v_addc_co_u32_e32 v1, vcc, 0, v7, vcc
	v_mov_b32_e32 v0, v188
	v_lshl_add_u64 v[4:5], v[2:3], 0, s[86:87]
	s_waitcnt vmcnt(0)
	v_lshlrev_b32_e32 v127, 16, v0
	v_add_co_u32_e32 v0, vcc, s74, v2
	s_nop 1
	v_addc_co_u32_e32 v1, vcc, 0, v3, vcc
	v_mov_b64_e32 v[0:1], v[190:191]
	v_mov_b64_e32 v[2:3], v[192:193]
	s_nop 0
	v_mov_b64_e32 v[4:5], v[194:195]
	v_mov_b64_e32 v[6:7], v[196:197]
	s_barrier
	s_waitcnt vmcnt(1)
	v_and_b32_e32 v130, 0xffff0000, v0
	s_waitcnt vmcnt(0)
	v_and_b32_e32 v131, 0xffff0000, v4
	v_lshlrev_b32_e32 v128, 16, v0
	v_lshlrev_b32_e32 v129, 16, v4
	v_pk_mul_f32 v[48:49], v[48:49], v[130:131]
	v_and_b32_e32 v4, 0xffff0000, v1
	v_pk_fma_f32 v[44:45], v[44:45], v[128:129], v[48:49]
	v_lshlrev_b32_e32 v48, 16, v1
	v_lshlrev_b32_e32 v49, 16, v5
	v_pk_fma_f32 v[42:43], v[42:43], v[48:49], v[44:45]
	v_and_b32_e32 v5, 0xffff0000, v5
	v_pk_fma_f32 v[0:1], v[40:41], v[4:5], v[42:43]
	v_lshlrev_b32_e32 v4, 16, v2
	v_lshlrev_b32_e32 v5, 16, v6
	v_pk_fma_f32 v[0:1], v[54:55], v[4:5], v[0:1]
	v_and_b32_e32 v5, 0xffff0000, v6
	v_and_b32_e32 v4, 0xffff0000, v2
	v_pk_fma_f32 v[0:1], v[52:53], v[4:5], v[0:1]
	v_lshlrev_b32_e32 v4, 16, v3
	v_lshlrev_b32_e32 v5, 16, v7
	v_pk_fma_f32 v[0:1], v[50:51], v[4:5], v[0:1]
	v_and_b32_e32 v5, 0xffff0000, v7
	v_and_b32_e32 v4, 0xffff0000, v3
	v_pk_fma_f32 v[0:1], v[46:47], v[4:5], v[0:1]
	v_add_f32_e32 v52, v120, v123
	v_add_f32_e32 v0, v108, v0
	v_add_f32_e32 v0, v0, v1
	v_min_f32_e32 v1, 0, v0
	v_mul_f32_e64 v0, |v0|, s94
	v_exp_f32_e32 v0, v0
	v_add_f32_e32 v53, v52, v125
	v_add_f32_e32 v54, v53, v126
	v_add_f32_e32 v0, 1.0, v0
	v_cmp_gt_f32_e32 vcc, s45, v0
	s_nop 1
	v_cndmask_b32_e64 v2, 0, 32, vcc
	v_ldexp_f32 v0, v0, v2
	v_log_f32_e32 v0, v0
	s_nop 0
	v_mul_f32_e32 v2, 0x3f317217, v0
	v_fma_f32 v2, v0, s29, -v2
	v_fmac_f32_e32 v2, 0x3377d1cf, v0
	v_fmac_f32_e32 v2, 0x3f317217, v0
	v_cmp_lt_f32_e64 s[30:31], |v0|, s95
	s_nop 1
	v_cndmask_b32_e64 v0, v0, v2, s[30:31]
	v_cndmask_b32_e32 v2, 0, v138, vcc
	v_sub_f32_e32 v0, v0, v2
	v_sub_f32_e32 v0, v1, v0
	v_mul_f32_e32 v0, 0x3d800000, v0
	v_cndmask_b32_e64 v2, 0, v0, s[24:25]
	v_add_f32_e32 v5, v54, v2
	ds_write_b32 v67, v5
	s_waitcnt lgkmcnt(0)
	s_barrier
	ds_read2st64_b32 v[6:7], v68 offset1:2
	ds_read2st64_b32 v[2:3], v68 offset0:4 offset1:6
	v_cndmask_b32_e64 v1, 0, v132, s[24:25]
	v_cndmask_b32_e64 v0, 0, v127, s[26:27]
	s_waitcnt lgkmcnt(1)
	v_add_f32_e32 v7, v6, v7
	s_waitcnt lgkmcnt(0)
	v_add_f32_e32 v4, v7, v2
	v_cndmask_b32_e64 v2, v4, v7, s[4:5]
	v_cndmask_b32_e64 v2, v2, v6, s[2:3]
	v_cndmask_b32_e64 v47, v2, 0, s[0:1]
	v_mov_b32_e32 v46, v3
	v_add_f32_e32 v45, v109, v47
	v_pk_add_f32 v[2:3], v[4:5], v[46:47]
	v_add_f32_e32 v44, v113, v47
	v_sub_f32_e32 v5, v2, v45
	v_mul_f32_e32 v5, 0x3fb8aa3b, v5
	v_exp_f32_e32 v40, v5
	v_sub_f32_e32 v5, v2, v44
	v_mul_f32_e32 v5, 0x3fb8aa3b, v5
	v_add_f32_e32 v43, v117, v47
	v_exp_f32_e32 v48, v5
	v_sub_f32_e32 v5, v2, v43
	v_mul_f32_e32 v5, 0x3fb8aa3b, v5
	v_exp_f32_e32 v41, v5
	v_add_f32_e32 v42, v120, v47
	v_sub_f32_e32 v5, v2, v42
	v_mul_f32_e32 v5, 0x3fb8aa3b, v5
	v_pk_mul_f32 v[50:51], v[56:57], v[40:41]
	v_add_f32_e32 v41, v52, v47
	v_exp_f32_e32 v49, v5
	v_sub_f32_e32 v5, v2, v41
	v_add_f32_e32 v40, v53, v47
	v_mul_f32_e32 v5, 0x3fb8aa3b, v5
	v_exp_f32_e32 v46, v5
	v_sub_f32_e32 v5, v2, v40
	v_mul_f32_e32 v5, 0x3fb8aa3b, v5
	v_exp_f32_e32 v52, v5
	v_add_f32_e32 v5, v47, v54
	v_sub_f32_e32 v53, v2, v3
	v_sub_f32_e32 v47, v2, v5
	v_mul_f32_e32 v53, 0x3fb8aa3b, v53
	v_mul_f32_e32 v47, 0x3fb8aa3b, v47
	v_exp_f32_e32 v53, v53
	v_exp_f32_e32 v47, v47
	v_pk_mul_f32 v[48:49], v[58:59], v[48:49]
	v_pk_mul_f32 v[52:53], v[0:1], v[52:53]
	v_pk_mul_f32 v[46:47], v[60:61], v[46:47]
	v_bfe_u32 v54, v53, 16, 1
	v_bfe_u32 v55, v52, 16, 1
	v_bfe_u32 v108, v49, 16, 1
	v_bfe_u32 v109, v48, 16, 1
	v_add3_u32 v52, v52, v55, s48
	v_add3_u32 v53, v53, v54, s48
	v_add3_u32 v54, v48, v109, s48
	v_add3_u32 v55, v49, v108, s48
	v_bfe_u32 v48, v46, 16, 1
	v_bfe_u32 v49, v47, 16, 1
	v_bfe_u32 v108, v50, 16, 1
	v_bfe_u32 v109, v51, 16, 1
	v_add3_u32 v47, v47, v49, s48
	v_add3_u32 v46, v46, v48, s48
	v_add3_u32 v48, v51, v109, s48
	v_add3_u32 v49, v50, v108, s48
	v_lshrrev_b32_e32 v46, 16, v46
	v_lshrrev_b32_e32 v47, 16, v47
	v_lshrrev_b32_e32 v50, 16, v49
	v_lshrrev_b32_e32 v51, 16, v48
	v_and_or_b32 v49, v53, s36, v47
	v_and_or_b32 v48, v52, s36, v46
	v_and_or_b32 v47, v55, s36, v51
	v_and_or_b32 v46, v54, s36, v50
	v_lshl_add_u64 v[50:51], v[38:39], 0, v[14:15]
	v_add_co_u32_e32 v50, vcc, 0x1000, v50
	s_nop 1
	v_addc_co_u32_e32 v51, vcc, 0, v51, vcc
	global_store_dwordx4 v[50:51], v[46:49], off
	s_and_saveexec_b64 s[30:31], s[8:9]
	s_cbranch_execz .LBB0_668
	v_mul_f32_e32 v2, 0x3fb8aa3b, v2
	v_exp_f32_e32 v2, v2
	v_lshl_add_u64 v[38:39], v[38:39], 0, v[8:9]
	v_add_co_u32_e32 v38, vcc, 0x2000, v38
	s_nop 1
	v_addc_co_u32_e32 v39, vcc, 0, v39, vcc
	global_store_dword v[38:39], v2, off offset:2048
